# P2b both tied paths: conv statistics butterfly via permlane32/16 swaps + DPP (1 LDS round trip instead of 63) and V^T epilogue dwordx4 stores
# speedup vs baseline: 1.0083x; 1.0058x over previous
; __device__ __forceinline__ void conv_unit(unsigned char* ws, LAS unsigned char* lds, int t0) {
;     ...
; #pragma unroll
;     for (int r = 0; r < 62; ++r) {
;         const int row = t0 - 15 + r;
;         unsigned yv = 0u;
;         if (row >= 0 && row < SEQ) yv = *(const unsigned*)(Y + (size_t)row * CONVW + c0);
;         y0[r] = bf_lo(yv); y1[r] = bf_hi(yv);
;     }
;     const f32x2 bias = *(const f32x2*)(conv_b + c0);
;     float a0[32], a1[32];
; #pragma unroll
;     for (int t = 0; t < 32; ++t) { a0[t] = bias[0]; a1[t] = bias[1]; }
; #pragma unroll
;     for (int j = 0; j < CONVK; ++j) {
;         const f32x2 w = *(const f32x2*)(conv_w + j * CONVW + c0);
; #pragma unroll
;         for (int t = 0; t < 32; ++t) { a0[t] += w[0] * y0[t + j]; a1[t] += w[1] * y1[t + j]; }
.LBB0_519:
	s_waitcnt vmcnt(0)
	v_lshlrev_b32_e32 v132, 16, v14
	v_and_b32_e32 v133, 0xffff0000, v14
	v_lshlrev_b32_e32 v14, 2, v12
	v_lshlrev_b32_e32 v124, 16, v113
	v_and_b32_e32 v125, 0xffff0000, v113
	v_lshlrev_b32_e32 v122, 16, v112
	v_and_b32_e32 v123, 0xffff0000, v112
	v_lshlrev_b32_e32 v120, 16, v111
	v_and_b32_e32 v121, 0xffff0000, v111
	v_lshlrev_b32_e32 v118, 16, v110
	v_and_b32_e32 v119, 0xffff0000, v110
	v_lshlrev_b32_e32 v116, 16, v109
	v_and_b32_e32 v117, 0xffff0000, v109
	v_lshlrev_b32_e32 v114, 16, v108
	v_and_b32_e32 v115, 0xffff0000, v108
	v_lshlrev_b32_e32 v112, 16, v107
	v_and_b32_e32 v113, 0xffff0000, v107
	v_lshlrev_b32_e32 v110, 16, v106
	v_and_b32_e32 v111, 0xffff0000, v106
	v_lshlrev_b32_e32 v108, 16, v105
	v_and_b32_e32 v109, 0xffff0000, v105
	v_lshlrev_b32_e32 v106, 16, v104
	v_and_b32_e32 v107, 0xffff0000, v104
	v_lshlrev_b32_e32 v104, 16, v81
	v_and_b32_e32 v105, 0xffff0000, v81
	v_lshlrev_b32_e32 v126, 16, v80
	v_and_b32_e32 v127, 0xffff0000, v80
	v_lshl_add_u64 v[80:81], s[20:21], 0, v[14:15]
	s_movk_i32 s19, 0x2000
	v_lshlrev_b32_e32 v128, 16, v59
	v_and_b32_e32 v129, 0xffff0000, v59
	v_lshlrev_b32_e32 v130, 16, v58
	v_and_b32_e32 v131, 0xffff0000, v58
	v_lshlrev_b32_e32 v58, 16, v134
	v_and_b32_e32 v59, 0xffff0000, v134
	v_add_co_u32_e32 v134, vcc, s19, v80
	global_load_dwordx2 v[174:175], v14, s[28:29]
	global_load_dwordx2 v[200:201], v14, s[20:21]
	v_addc_co_u32_e32 v135, vcc, 0, v81, vcc
	s_movk_i32 s19, 0x4000
	v_add_co_u32_e32 v198, vcc, s19, v80
	global_load_dwordx2 v[202:203], v[134:135], off offset:-4096
	global_load_dwordx2 v[204:205], v[134:135], off
	v_addc_co_u32_e32 v199, vcc, 0, v81, vcc
	global_load_dwordx2 v[206:207], v[198:199], off offset:-4096
	v_lshlrev_b32_e32 v68, 16, v69
	v_and_b32_e32 v69, 0xffff0000, v69
	v_lshlrev_b32_e32 v70, 16, v71
	v_and_b32_e32 v71, 0xffff0000, v71
	v_lshlrev_b32_e32 v72, 16, v73
	v_and_b32_e32 v73, 0xffff0000, v73
	v_lshlrev_b32_e32 v74, 16, v75
	v_and_b32_e32 v75, 0xffff0000, v75
	v_lshlrev_b32_e32 v76, 16, v77
	v_and_b32_e32 v77, 0xffff0000, v77
	v_lshlrev_b32_e32 v78, 16, v79
	v_and_b32_e32 v79, 0xffff0000, v79
	v_lshlrev_b32_e32 v82, 16, v83
	v_and_b32_e32 v83, 0xffff0000, v83
	v_lshlrev_b32_e32 v84, 16, v85
	v_and_b32_e32 v85, 0xffff0000, v85
	v_lshlrev_b32_e32 v86, 16, v87
	v_and_b32_e32 v87, 0xffff0000, v87
	v_lshlrev_b32_e32 v88, 16, v89
	v_and_b32_e32 v89, 0xffff0000, v89
	v_lshlrev_b32_e32 v90, 16, v91
	v_and_b32_e32 v91, 0xffff0000, v91
	v_lshlrev_b32_e32 v92, 16, v93
	v_and_b32_e32 v93, 0xffff0000, v93
	v_lshlrev_b32_e32 v94, 16, v95
	v_and_b32_e32 v95, 0xffff0000, v95
	v_lshlrev_b32_e32 v96, 16, v97
	v_and_b32_e32 v97, 0xffff0000, v97
	v_lshlrev_b32_e32 v98, 16, v99
	v_and_b32_e32 v99, 0xffff0000, v99
	v_lshlrev_b32_e32 v100, 16, v101
	v_and_b32_e32 v101, 0xffff0000, v101
	v_lshlrev_b32_e32 v102, 16, v103
	v_and_b32_e32 v103, 0xffff0000, v103
	v_lshlrev_b32_e32 v66, 16, v67
	v_and_b32_e32 v67, 0xffff0000, v67
	s_movk_i32 s19, 0x6000
	v_lshlrev_b32_e32 v64, 16, v65
	v_and_b32_e32 v65, 0xffff0000, v65
	global_load_dwordx2 v[198:199], v[198:199], off
	v_lshlrev_b32_e32 v62, 16, v63
	v_and_b32_e32 v63, 0xffff0000, v63
	v_lshlrev_b32_e32 v60, 16, v61
	v_and_b32_e32 v61, 0xffff0000, v61
	v_lshlrev_b32_e32 v56, 16, v57
	v_and_b32_e32 v57, 0xffff0000, v57
	v_lshlrev_b32_e32 v54, 16, v55
	v_and_b32_e32 v55, 0xffff0000, v55
	v_lshlrev_b32_e32 v52, 16, v53
	v_and_b32_e32 v53, 0xffff0000, v53
	v_lshlrev_b32_e32 v50, 16, v51
	v_and_b32_e32 v51, 0xffff0000, v51
	v_lshlrev_b32_e32 v48, 16, v49
	v_and_b32_e32 v49, 0xffff0000, v49
	v_lshlrev_b32_e32 v46, 16, v47
	v_and_b32_e32 v47, 0xffff0000, v47
	v_lshlrev_b32_e32 v44, 16, v45
	v_and_b32_e32 v45, 0xffff0000, v45
	v_lshlrev_b32_e32 v42, 16, v43
	v_and_b32_e32 v43, 0xffff0000, v43
	v_lshlrev_b32_e32 v40, 16, v41
	v_and_b32_e32 v41, 0xffff0000, v41
	v_lshlrev_b32_e32 v38, 16, v39
	v_and_b32_e32 v39, 0xffff0000, v39
	v_lshlrev_b32_e32 v36, 16, v37
	v_and_b32_e32 v37, 0xffff0000, v37
	v_lshlrev_b32_e32 v34, 16, v35
	v_and_b32_e32 v35, 0xffff0000, v35
	v_lshlrev_b32_e32 v32, 16, v33
	v_and_b32_e32 v33, 0xffff0000, v33
	s_waitcnt vmcnt(4)
	v_pk_fma_f32 v[132:133], v[200:201], v[132:133], v[174:175]
	v_pk_fma_f32 v[134:135], v[200:201], v[102:103], v[174:175]
	v_pk_fma_f32 v[136:137], v[200:201], v[100:101], v[174:175]
	v_pk_fma_f32 v[138:139], v[200:201], v[98:99], v[174:175]
	v_pk_fma_f32 v[140:141], v[200:201], v[96:97], v[174:175]
	s_waitcnt vmcnt(3)
	v_pk_fma_f32 v[132:133], v[202:203], v[130:131], v[132:133]
	v_pk_fma_f32 v[130:131], v[200:201], v[130:131], v[174:175]
	s_waitcnt vmcnt(2)
	v_pk_fma_f32 v[132:133], v[204:205], v[128:129], v[132:133]
	v_pk_fma_f32 v[130:131], v[202:203], v[128:129], v[130:131]
	v_pk_fma_f32 v[128:129], v[200:201], v[128:129], v[174:175]
	s_waitcnt vmcnt(1)
; __device__ __forceinline__ void conv_unit(unsigned char* ws, LAS unsigned char* lds, int t0) {
;     ...
;     for (int j = 0; j < CONVK; ++j) {
;         const f32x2 w = *(const f32x2*)(conv_w + j * CONVW + c0);
; #pragma unroll
;         for (int t = 0; t < 32; ++t) { a0[t] += w[0] * y0[t + j]; a1[t] += w[1] * y1[t + j]; }
	v_pk_fma_f32 v[196:197], v[206:207], v[126:127], v[132:133]
	v_pk_fma_f32 v[130:131], v[204:205], v[126:127], v[130:131]
	v_pk_fma_f32 v[128:129], v[202:203], v[126:127], v[128:129]
	v_pk_fma_f32 v[126:127], v[200:201], v[126:127], v[174:175]
	v_pk_fma_f32 v[128:129], v[204:205], v[104:105], v[128:129]
	v_pk_fma_f32 v[126:127], v[202:203], v[104:105], v[126:127]
	v_pk_fma_f32 v[194:195], v[206:207], v[104:105], v[130:131]
	v_pk_fma_f32 v[126:127], v[204:205], v[106:107], v[126:127]
	v_pk_fma_f32 v[192:193], v[206:207], v[106:107], v[128:129]
	v_pk_fma_f32 v[190:191], v[206:207], v[108:109], v[126:127]
	v_pk_fma_f32 v[126:127], v[200:201], v[104:105], v[174:175]
	v_pk_fma_f32 v[128:129], v[200:201], v[120:121], v[174:175]
	v_pk_fma_f32 v[126:127], v[202:203], v[106:107], v[126:127]
	v_pk_fma_f32 v[130:131], v[200:201], v[122:123], v[174:175]
	v_pk_fma_f32 v[126:127], v[204:205], v[108:109], v[126:127]
	v_pk_fma_f32 v[132:133], v[200:201], v[124:125], v[174:175]
	v_pk_fma_f32 v[188:189], v[206:207], v[110:111], v[126:127]
	v_pk_fma_f32 v[126:127], v[200:201], v[106:107], v[174:175]
	v_pk_fma_f32 v[142:143], v[200:201], v[94:95], v[174:175]
	v_pk_fma_f32 v[126:127], v[202:203], v[108:109], v[126:127]
	v_pk_fma_f32 v[144:145], v[200:201], v[92:93], v[174:175]
	v_pk_fma_f32 v[126:127], v[204:205], v[110:111], v[126:127]
	v_pk_fma_f32 v[146:147], v[200:201], v[90:91], v[174:175]
	v_pk_fma_f32 v[186:187], v[206:207], v[112:113], v[126:127]
	v_pk_fma_f32 v[126:127], v[200:201], v[108:109], v[174:175]
	v_pk_fma_f32 v[148:149], v[200:201], v[88:89], v[174:175]
	v_pk_fma_f32 v[126:127], v[202:203], v[110:111], v[126:127]
	v_pk_fma_f32 v[150:151], v[200:201], v[86:87], v[174:175]
	v_pk_fma_f32 v[126:127], v[204:205], v[112:113], v[126:127]
	v_pk_fma_f32 v[152:153], v[200:201], v[84:85], v[174:175]
	v_pk_fma_f32 v[184:185], v[206:207], v[114:115], v[126:127]
	v_pk_fma_f32 v[126:127], v[200:201], v[110:111], v[174:175]
	v_pk_fma_f32 v[154:155], v[200:201], v[82:83], v[174:175]
	v_pk_fma_f32 v[126:127], v[202:203], v[112:113], v[126:127]
	v_pk_fma_f32 v[156:157], v[200:201], v[78:79], v[174:175]
	v_pk_fma_f32 v[126:127], v[204:205], v[114:115], v[126:127]
	v_pk_fma_f32 v[158:159], v[200:201], v[76:77], v[174:175]
	v_pk_fma_f32 v[182:183], v[206:207], v[116:117], v[126:127]
	v_pk_fma_f32 v[126:127], v[200:201], v[112:113], v[174:175]
	v_pk_fma_f32 v[168:169], v[200:201], v[74:75], v[174:175]
	v_pk_fma_f32 v[126:127], v[202:203], v[114:115], v[126:127]
	v_pk_fma_f32 v[170:171], v[200:201], v[72:73], v[174:175]
	v_pk_fma_f32 v[126:127], v[204:205], v[116:117], v[126:127]
	v_pk_fma_f32 v[172:173], v[200:201], v[70:71], v[174:175]
	v_pk_fma_f32 v[180:181], v[206:207], v[118:119], v[126:127]
	v_pk_fma_f32 v[126:127], v[200:201], v[114:115], v[174:175]
	v_pk_fma_f32 v[128:129], v[202:203], v[122:123], v[128:129]
	v_pk_fma_f32 v[126:127], v[202:203], v[116:117], v[126:127]
	v_pk_fma_f32 v[130:131], v[202:203], v[124:125], v[130:131]
	v_pk_fma_f32 v[126:127], v[204:205], v[118:119], v[126:127]
	v_pk_fma_f32 v[132:133], v[202:203], v[102:103], v[132:133]
	v_pk_fma_f32 v[178:179], v[206:207], v[120:121], v[126:127]
	v_pk_fma_f32 v[126:127], v[200:201], v[116:117], v[174:175]
	v_pk_fma_f32 v[134:135], v[202:203], v[100:101], v[134:135]
	v_pk_fma_f32 v[126:127], v[202:203], v[118:119], v[126:127]
	v_pk_fma_f32 v[136:137], v[202:203], v[98:99], v[136:137]
	v_pk_fma_f32 v[126:127], v[204:205], v[120:121], v[126:127]
	v_pk_fma_f32 v[138:139], v[202:203], v[96:97], v[138:139]
	v_pk_fma_f32 v[176:177], v[206:207], v[122:123], v[126:127]
	v_pk_fma_f32 v[126:127], v[200:201], v[118:119], v[174:175]
	v_pk_fma_f32 v[174:175], v[200:201], v[68:69], v[174:175]
	v_pk_fma_f32 v[126:127], v[202:203], v[120:121], v[126:127]
	v_pk_fma_f32 v[140:141], v[202:203], v[94:95], v[140:141]
	v_pk_fma_f32 v[142:143], v[202:203], v[92:93], v[142:143]
	v_pk_fma_f32 v[144:145], v[202:203], v[90:91], v[144:145]
	v_pk_fma_f32 v[146:147], v[202:203], v[88:89], v[146:147]
	v_pk_fma_f32 v[148:149], v[202:203], v[86:87], v[148:149]
	v_pk_fma_f32 v[150:151], v[202:203], v[84:85], v[150:151]
	v_pk_fma_f32 v[152:153], v[202:203], v[82:83], v[152:153]
	v_pk_fma_f32 v[154:155], v[202:203], v[78:79], v[154:155]
	v_pk_fma_f32 v[156:157], v[202:203], v[76:77], v[156:157]
	v_pk_fma_f32 v[158:159], v[202:203], v[74:75], v[158:159]
	v_pk_fma_f32 v[168:169], v[202:203], v[72:73], v[168:169]
	v_pk_fma_f32 v[170:171], v[202:203], v[70:71], v[170:171]
	v_pk_fma_f32 v[172:173], v[202:203], v[68:69], v[172:173]
	v_pk_fma_f32 v[174:175], v[202:203], v[66:67], v[174:175]
	v_add_co_u32_e32 v202, vcc, s19, v80
	v_pk_fma_f32 v[126:127], v[204:205], v[122:123], v[126:127]
	v_pk_fma_f32 v[128:129], v[204:205], v[124:125], v[128:129]
	v_pk_fma_f32 v[130:131], v[204:205], v[102:103], v[130:131]
	v_pk_fma_f32 v[132:133], v[204:205], v[100:101], v[132:133]
	v_pk_fma_f32 v[134:135], v[204:205], v[98:99], v[134:135]
	v_pk_fma_f32 v[136:137], v[204:205], v[96:97], v[136:137]
	v_pk_fma_f32 v[138:139], v[204:205], v[94:95], v[138:139]
	v_pk_fma_f32 v[140:141], v[204:205], v[92:93], v[140:141]
	v_pk_fma_f32 v[142:143], v[204:205], v[90:91], v[142:143]
	v_pk_fma_f32 v[144:145], v[204:205], v[88:89], v[144:145]
	v_pk_fma_f32 v[146:147], v[204:205], v[86:87], v[146:147]
	v_pk_fma_f32 v[148:149], v[204:205], v[84:85], v[148:149]
	v_pk_fma_f32 v[150:151], v[204:205], v[82:83], v[150:151]
	v_pk_fma_f32 v[152:153], v[204:205], v[78:79], v[152:153]
	v_pk_fma_f32 v[154:155], v[204:205], v[76:77], v[154:155]
	v_pk_fma_f32 v[156:157], v[204:205], v[74:75], v[156:157]
	v_pk_fma_f32 v[158:159], v[204:205], v[72:73], v[158:159]
; __device__ __forceinline__ void conv_unit(unsigned char* ws, LAS unsigned char* lds, int t0) {
;     ...
;     for (int j = 0; j < CONVK; ++j) {
;         const f32x2 w = *(const f32x2*)(conv_w + j * CONVW + c0);
; #pragma unroll
;         for (int t = 0; t < 32; ++t) { a0[t] += w[0] * y0[t + j]; a1[t] += w[1] * y1[t + j]; }
	v_pk_fma_f32 v[168:169], v[204:205], v[70:71], v[168:169]
	v_pk_fma_f32 v[170:171], v[204:205], v[68:69], v[170:171]
	v_pk_fma_f32 v[172:173], v[204:205], v[66:67], v[172:173]
	v_pk_fma_f32 v[174:175], v[204:205], v[64:65], v[174:175]
	v_addc_co_u32_e32 v203, vcc, 0, v81, vcc
	s_mov_b32 s19, 0x8000
	v_pk_fma_f32 v[126:127], v[206:207], v[124:125], v[126:127]
	v_pk_fma_f32 v[128:129], v[206:207], v[102:103], v[128:129]
	v_pk_fma_f32 v[130:131], v[206:207], v[100:101], v[130:131]
	v_pk_fma_f32 v[132:133], v[206:207], v[98:99], v[132:133]
	v_pk_fma_f32 v[134:135], v[206:207], v[96:97], v[134:135]
	v_pk_fma_f32 v[136:137], v[206:207], v[94:95], v[136:137]
	v_pk_fma_f32 v[138:139], v[206:207], v[92:93], v[138:139]
	v_pk_fma_f32 v[140:141], v[206:207], v[90:91], v[140:141]
	v_pk_fma_f32 v[142:143], v[206:207], v[88:89], v[142:143]
	v_pk_fma_f32 v[144:145], v[206:207], v[86:87], v[144:145]
	v_pk_fma_f32 v[146:147], v[206:207], v[84:85], v[146:147]
	v_pk_fma_f32 v[148:149], v[206:207], v[82:83], v[148:149]
	v_pk_fma_f32 v[150:151], v[206:207], v[78:79], v[150:151]
	v_pk_fma_f32 v[152:153], v[206:207], v[76:77], v[152:153]
	v_pk_fma_f32 v[154:155], v[206:207], v[74:75], v[154:155]
	v_pk_fma_f32 v[156:157], v[206:207], v[72:73], v[156:157]
	v_pk_fma_f32 v[158:159], v[206:207], v[70:71], v[158:159]
	v_pk_fma_f32 v[168:169], v[206:207], v[68:69], v[168:169]
	v_pk_fma_f32 v[170:171], v[206:207], v[66:67], v[170:171]
	v_pk_fma_f32 v[172:173], v[206:207], v[64:65], v[172:173]
	v_pk_fma_f32 v[174:175], v[206:207], v[62:63], v[174:175]
	global_load_dwordx2 v[200:201], v[202:203], off offset:-4096
	s_nop 0
	global_load_dwordx2 v[202:203], v[202:203], off
	v_add_co_u32_e32 v206, vcc, s19, v80
	s_mov_b32 s19, 0xa000
	s_nop 0
	v_addc_co_u32_e32 v207, vcc, 0, v81, vcc
	global_load_dwordx2 v[204:205], v[206:207], off offset:-4096
	s_nop 0
	global_load_dwordx2 v[206:207], v[206:207], off
	v_add_co_u32_e32 v210, vcc, s19, v80
	s_mov_b32 s19, 0xc000
	s_nop 0
	v_addc_co_u32_e32 v211, vcc, 0, v81, vcc
	global_load_dwordx2 v[208:209], v[210:211], off offset:-4096
	s_nop 0
	global_load_dwordx2 v[210:211], v[210:211], off
	v_add_co_u32_e32 v214, vcc, s19, v80
	s_mov_b32 s19, 0xe000
	s_nop 0
	v_addc_co_u32_e32 v215, vcc, 0, v81, vcc
	global_load_dwordx2 v[212:213], v[214:215], off offset:-4096
	s_nop 0
	global_load_dwordx2 v[214:215], v[214:215], off
	v_add_co_u32_e32 v218, vcc, s19, v80
	s_waitcnt vmcnt(8)
	v_pk_fma_f32 v[104:105], v[198:199], v[104:105], v[196:197]
	v_addc_co_u32_e32 v219, vcc, 0, v81, vcc
	global_load_dwordx2 v[216:217], v[218:219], off offset:-4096
	s_nop 0
	global_load_dwordx2 v[218:219], v[218:219], off
	s_mov_b32 s19, 0x10000
	v_pk_fma_f32 v[126:127], v[198:199], v[102:103], v[126:127]
	v_pk_fma_f32 v[128:129], v[198:199], v[100:101], v[128:129]
	v_pk_fma_f32 v[130:131], v[198:199], v[98:99], v[130:131]
	v_pk_fma_f32 v[132:133], v[198:199], v[96:97], v[132:133]
	v_pk_fma_f32 v[134:135], v[198:199], v[94:95], v[134:135]
	v_pk_fma_f32 v[136:137], v[198:199], v[92:93], v[136:137]
	v_pk_fma_f32 v[138:139], v[198:199], v[90:91], v[138:139]
	v_pk_fma_f32 v[140:141], v[198:199], v[88:89], v[140:141]
	v_pk_fma_f32 v[142:143], v[198:199], v[86:87], v[142:143]
	v_pk_fma_f32 v[144:145], v[198:199], v[84:85], v[144:145]
	v_pk_fma_f32 v[146:147], v[198:199], v[82:83], v[146:147]
	v_pk_fma_f32 v[148:149], v[198:199], v[78:79], v[148:149]
	v_pk_fma_f32 v[150:151], v[198:199], v[76:77], v[150:151]
	v_pk_fma_f32 v[152:153], v[198:199], v[74:75], v[152:153]
	v_pk_fma_f32 v[154:155], v[198:199], v[72:73], v[154:155]
	v_pk_fma_f32 v[156:157], v[198:199], v[70:71], v[156:157]
	v_pk_fma_f32 v[158:159], v[198:199], v[68:69], v[158:159]
	v_pk_fma_f32 v[168:169], v[198:199], v[66:67], v[168:169]
	v_pk_fma_f32 v[170:171], v[198:199], v[64:65], v[170:171]
	v_pk_fma_f32 v[172:173], v[198:199], v[62:63], v[172:173]
	v_pk_fma_f32 v[174:175], v[198:199], v[60:61], v[174:175]
	v_lshlrev_b32_e32 v30, 16, v31
	v_and_b32_e32 v31, 0xffff0000, v31
	v_lshlrev_b32_e32 v28, 16, v29
	v_and_b32_e32 v29, 0xffff0000, v29
	v_lshlrev_b32_e32 v26, 16, v27
	v_and_b32_e32 v27, 0xffff0000, v27
	v_lshlrev_b32_e32 v24, 16, v25
	v_and_b32_e32 v25, 0xffff0000, v25
	v_lshlrev_b32_e32 v22, 16, v23
	v_and_b32_e32 v23, 0xffff0000, v23
	v_lshlrev_b32_e32 v20, 16, v21
	v_and_b32_e32 v21, 0xffff0000, v21
	v_lshlrev_b32_e32 v10, 16, v11
	v_and_b32_e32 v11, 0xffff0000, v11
	v_lshlrev_b32_e32 v8, 16, v9
	v_and_b32_e32 v9, 0xffff0000, v9
	v_lshlrev_b32_e32 v6, 16, v7
	v_and_b32_e32 v7, 0xffff0000, v7
	v_lshlrev_b32_e32 v4, 16, v5
	v_and_b32_e32 v5, 0xffff0000, v5
	v_lshlrev_b32_e32 v2, 16, v3
	v_and_b32_e32 v3, 0xffff0000, v3
	v_lshlrev_b32_e32 v0, 16, v1
	v_and_b32_e32 v1, 0xffff0000, v1
	s_add_i32 s36, s24, 15
	s_add_i32 s30, s24, 16
	s_lshl_b64 s[20:21], s[36:37], 11
	s_mov_b32 s31, s37
	s_add_i32 s96, s24, 17
	s_mov_b32 s97, s37
	s_add_i32 s94, s24, 18
	s_mov_b32 s95, s37
	s_waitcnt vmcnt(9)
	v_pk_fma_f32 v[104:105], v[200:201], v[106:107], v[104:105]
	v_pk_fma_f32 v[106:107], v[198:199], v[106:107], v[194:195]
	s_waitcnt vmcnt(8)
	v_pk_fma_f32 v[104:105], v[202:203], v[108:109], v[104:105]
	v_pk_fma_f32 v[106:107], v[200:201], v[108:109], v[106:107]
	v_pk_fma_f32 v[108:109], v[198:199], v[108:109], v[192:193]
	v_pk_fma_f32 v[106:107], v[202:203], v[110:111], v[106:107]
	s_waitcnt vmcnt(7)
	v_pk_fma_f32 v[104:105], v[204:205], v[110:111], v[104:105]
	v_pk_fma_f32 v[108:109], v[200:201], v[110:111], v[108:109]
	v_pk_fma_f32 v[110:111], v[198:199], v[110:111], v[190:191]
	s_waitcnt vmcnt(6)
; __device__ __forceinline__ void conv_unit(unsigned char* ws, LAS unsigned char* lds, int t0) {
;     ...
;     for (int j = 0; j < CONVK; ++j) {
;         const f32x2 w = *(const f32x2*)(conv_w + j * CONVW + c0);
; #pragma unroll
;         for (int t = 0; t < 32; ++t) { a0[t] += w[0] * y0[t + j]; a1[t] += w[1] * y1[t + j]; }
	v_pk_fma_f32 v[104:105], v[206:207], v[112:113], v[104:105]
	v_pk_fma_f32 v[106:107], v[204:205], v[112:113], v[106:107]
	v_pk_fma_f32 v[108:109], v[202:203], v[112:113], v[108:109]
	v_pk_fma_f32 v[110:111], v[200:201], v[112:113], v[110:111]
	v_pk_fma_f32 v[112:113], v[198:199], v[112:113], v[188:189]
	s_waitcnt vmcnt(5)
	v_pk_fma_f32 v[104:105], v[208:209], v[114:115], v[104:105]
	v_pk_fma_f32 v[106:107], v[206:207], v[114:115], v[106:107]
	v_pk_fma_f32 v[108:109], v[204:205], v[114:115], v[108:109]
	v_pk_fma_f32 v[110:111], v[202:203], v[114:115], v[110:111]
	v_pk_fma_f32 v[112:113], v[200:201], v[114:115], v[112:113]
	v_pk_fma_f32 v[114:115], v[198:199], v[114:115], v[186:187]
	s_waitcnt vmcnt(4)
	v_pk_fma_f32 v[104:105], v[210:211], v[116:117], v[104:105]
	v_pk_fma_f32 v[106:107], v[208:209], v[116:117], v[106:107]
	v_pk_fma_f32 v[108:109], v[206:207], v[116:117], v[108:109]
	v_pk_fma_f32 v[110:111], v[204:205], v[116:117], v[110:111]
	v_pk_fma_f32 v[112:113], v[202:203], v[116:117], v[112:113]
	v_pk_fma_f32 v[114:115], v[200:201], v[116:117], v[114:115]
	v_pk_fma_f32 v[116:117], v[198:199], v[116:117], v[184:185]
	s_waitcnt vmcnt(3)
	v_pk_fma_f32 v[104:105], v[212:213], v[118:119], v[104:105]
	v_pk_fma_f32 v[106:107], v[210:211], v[118:119], v[106:107]
	v_pk_fma_f32 v[108:109], v[208:209], v[118:119], v[108:109]
	v_pk_fma_f32 v[110:111], v[206:207], v[118:119], v[110:111]
	v_pk_fma_f32 v[112:113], v[204:205], v[118:119], v[112:113]
	v_pk_fma_f32 v[114:115], v[202:203], v[118:119], v[114:115]
	v_pk_fma_f32 v[116:117], v[200:201], v[118:119], v[116:117]
	v_pk_fma_f32 v[118:119], v[198:199], v[118:119], v[182:183]
	s_waitcnt vmcnt(2)
	v_pk_fma_f32 v[104:105], v[214:215], v[120:121], v[104:105]
	v_pk_fma_f32 v[106:107], v[212:213], v[120:121], v[106:107]
	v_pk_fma_f32 v[108:109], v[210:211], v[120:121], v[108:109]
	v_pk_fma_f32 v[110:111], v[208:209], v[120:121], v[110:111]
	v_pk_fma_f32 v[112:113], v[206:207], v[120:121], v[112:113]
	v_pk_fma_f32 v[114:115], v[204:205], v[120:121], v[114:115]
	v_pk_fma_f32 v[116:117], v[202:203], v[120:121], v[116:117]
	v_pk_fma_f32 v[118:119], v[200:201], v[120:121], v[118:119]
	v_pk_fma_f32 v[120:121], v[198:199], v[120:121], v[180:181]
	s_waitcnt vmcnt(1)
	v_pk_fma_f32 v[104:105], v[216:217], v[122:123], v[104:105]
	v_pk_fma_f32 v[106:107], v[214:215], v[122:123], v[106:107]
	v_pk_fma_f32 v[108:109], v[212:213], v[122:123], v[108:109]
	v_pk_fma_f32 v[110:111], v[210:211], v[122:123], v[110:111]
	v_pk_fma_f32 v[112:113], v[208:209], v[122:123], v[112:113]
	v_pk_fma_f32 v[114:115], v[206:207], v[122:123], v[114:115]
	v_pk_fma_f32 v[116:117], v[204:205], v[122:123], v[116:117]
	v_pk_fma_f32 v[118:119], v[202:203], v[122:123], v[118:119]
	v_pk_fma_f32 v[120:121], v[200:201], v[122:123], v[120:121]
	v_pk_fma_f32 v[122:123], v[198:199], v[122:123], v[178:179]
	v_add_co_u32_e32 v178, vcc, s19, v80
	s_mov_b32 s19, 0x12000
	s_nop 0
	v_addc_co_u32_e32 v179, vcc, 0, v81, vcc
	v_add_co_u32_e32 v182, vcc, s19, v80
	s_waitcnt vmcnt(0)
	v_pk_fma_f32 v[104:105], v[218:219], v[124:125], v[104:105]
	v_pk_fma_f32 v[106:107], v[216:217], v[124:125], v[106:107]
	v_pk_fma_f32 v[108:109], v[214:215], v[124:125], v[108:109]
	v_pk_fma_f32 v[110:111], v[212:213], v[124:125], v[110:111]
	v_pk_fma_f32 v[112:113], v[210:211], v[124:125], v[112:113]
	v_pk_fma_f32 v[114:115], v[208:209], v[124:125], v[114:115]
	v_pk_fma_f32 v[116:117], v[206:207], v[124:125], v[116:117]
	v_pk_fma_f32 v[118:119], v[204:205], v[124:125], v[118:119]
	v_pk_fma_f32 v[120:121], v[202:203], v[124:125], v[120:121]
	v_pk_fma_f32 v[122:123], v[200:201], v[124:125], v[122:123]
	v_pk_fma_f32 v[124:125], v[198:199], v[124:125], v[176:177]
	global_load_dwordx2 v[176:177], v[178:179], off offset:-4096
	s_nop 0
	global_load_dwordx2 v[178:179], v[178:179], off
	v_addc_co_u32_e32 v183, vcc, 0, v81, vcc
	s_mov_b32 s19, 0x14000
	v_add_co_u32_e32 v186, vcc, s19, v80
	global_load_dwordx2 v[180:181], v[182:183], off offset:-4096
	s_nop 0
	global_load_dwordx2 v[182:183], v[182:183], off
	v_addc_co_u32_e32 v187, vcc, 0, v81, vcc
	s_mov_b32 s19, 0x16000
	v_add_co_u32_e32 v190, vcc, s19, v80
	global_load_dwordx2 v[184:185], v[186:187], off offset:-4096
	s_nop 0
	global_load_dwordx2 v[186:187], v[186:187], off
	v_addc_co_u32_e32 v191, vcc, 0, v81, vcc
	s_mov_b32 s19, 0x18000
	v_add_co_u32_e32 v194, vcc, s19, v80
	global_load_dwordx2 v[188:189], v[190:191], off offset:-4096
	s_nop 0
	global_load_dwordx2 v[190:191], v[190:191], off
	v_addc_co_u32_e32 v195, vcc, 0, v81, vcc
	s_mov_b32 s19, 0x1a000
	v_add_co_u32_e32 v196, vcc, s19, v80
	global_load_dwordx2 v[192:193], v[194:195], off offset:-4096
	s_nop 0
	global_load_dwordx2 v[194:195], v[194:195], off
	v_addc_co_u32_e32 v197, vcc, 0, v81, vcc
	global_load_dwordx2 v[198:199], v[196:197], off offset:-4096
	v_pk_fma_f32 v[106:107], v[218:219], v[102:103], v[106:107]
	v_pk_fma_f32 v[108:109], v[216:217], v[102:103], v[108:109]
	v_pk_fma_f32 v[110:111], v[214:215], v[102:103], v[110:111]
	v_pk_fma_f32 v[112:113], v[212:213], v[102:103], v[112:113]
	v_pk_fma_f32 v[114:115], v[210:211], v[102:103], v[114:115]
	v_pk_fma_f32 v[116:117], v[208:209], v[102:103], v[116:117]
	v_pk_fma_f32 v[118:119], v[206:207], v[102:103], v[118:119]
	v_pk_fma_f32 v[120:121], v[204:205], v[102:103], v[120:121]
	v_pk_fma_f32 v[122:123], v[202:203], v[102:103], v[122:123]
	v_pk_fma_f32 v[124:125], v[200:201], v[102:103], v[124:125]
	v_pk_fma_f32 v[108:109], v[218:219], v[100:101], v[108:109]
	v_pk_fma_f32 v[110:111], v[216:217], v[100:101], v[110:111]
	v_pk_fma_f32 v[112:113], v[214:215], v[100:101], v[112:113]
	v_pk_fma_f32 v[114:115], v[212:213], v[100:101], v[114:115]
; __device__ __forceinline__ void conv_unit(unsigned char* ws, LAS unsigned char* lds, int t0) {
;     ...
;     for (int j = 0; j < CONVK; ++j) {
;         const f32x2 w = *(const f32x2*)(conv_w + j * CONVW + c0);
; #pragma unroll
;         for (int t = 0; t < 32; ++t) { a0[t] += w[0] * y0[t + j]; a1[t] += w[1] * y1[t + j]; }
	v_pk_fma_f32 v[116:117], v[210:211], v[100:101], v[116:117]
	v_pk_fma_f32 v[118:119], v[208:209], v[100:101], v[118:119]
	v_pk_fma_f32 v[120:121], v[206:207], v[100:101], v[120:121]
	v_pk_fma_f32 v[122:123], v[204:205], v[100:101], v[122:123]
	v_pk_fma_f32 v[124:125], v[202:203], v[100:101], v[124:125]
	v_pk_fma_f32 v[126:127], v[200:201], v[100:101], v[126:127]
	v_pk_fma_f32 v[110:111], v[218:219], v[98:99], v[110:111]
	v_pk_fma_f32 v[112:113], v[216:217], v[98:99], v[112:113]
	v_pk_fma_f32 v[114:115], v[214:215], v[98:99], v[114:115]
	v_pk_fma_f32 v[116:117], v[212:213], v[98:99], v[116:117]
	v_pk_fma_f32 v[118:119], v[210:211], v[98:99], v[118:119]
	v_pk_fma_f32 v[120:121], v[208:209], v[98:99], v[120:121]
	v_pk_fma_f32 v[122:123], v[206:207], v[98:99], v[122:123]
	v_pk_fma_f32 v[124:125], v[204:205], v[98:99], v[124:125]
	v_pk_fma_f32 v[126:127], v[202:203], v[98:99], v[126:127]
	v_pk_fma_f32 v[128:129], v[200:201], v[98:99], v[128:129]
	v_pk_fma_f32 v[112:113], v[218:219], v[96:97], v[112:113]
	v_pk_fma_f32 v[114:115], v[216:217], v[96:97], v[114:115]
	v_pk_fma_f32 v[116:117], v[214:215], v[96:97], v[116:117]
	v_pk_fma_f32 v[118:119], v[212:213], v[96:97], v[118:119]
	v_pk_fma_f32 v[120:121], v[210:211], v[96:97], v[120:121]
	v_pk_fma_f32 v[122:123], v[208:209], v[96:97], v[122:123]
	v_pk_fma_f32 v[124:125], v[206:207], v[96:97], v[124:125]
	v_pk_fma_f32 v[126:127], v[204:205], v[96:97], v[126:127]
	v_pk_fma_f32 v[128:129], v[202:203], v[96:97], v[128:129]
	v_pk_fma_f32 v[130:131], v[200:201], v[96:97], v[130:131]
	v_pk_fma_f32 v[114:115], v[218:219], v[94:95], v[114:115]
	v_pk_fma_f32 v[116:117], v[216:217], v[94:95], v[116:117]
	v_pk_fma_f32 v[118:119], v[214:215], v[94:95], v[118:119]
	v_pk_fma_f32 v[120:121], v[212:213], v[94:95], v[120:121]
	v_pk_fma_f32 v[122:123], v[210:211], v[94:95], v[122:123]
	v_pk_fma_f32 v[124:125], v[208:209], v[94:95], v[124:125]
	v_pk_fma_f32 v[126:127], v[206:207], v[94:95], v[126:127]
	v_pk_fma_f32 v[128:129], v[204:205], v[94:95], v[128:129]
	v_pk_fma_f32 v[130:131], v[202:203], v[94:95], v[130:131]
	v_pk_fma_f32 v[132:133], v[200:201], v[94:95], v[132:133]
	v_pk_fma_f32 v[116:117], v[218:219], v[92:93], v[116:117]
	s_waitcnt vmcnt(10)
	v_pk_fma_f32 v[102:103], v[176:177], v[102:103], v[104:105]
	v_pk_fma_f32 v[118:119], v[216:217], v[92:93], v[118:119]
	s_waitcnt vmcnt(9)
	v_pk_fma_f32 v[102:103], v[178:179], v[100:101], v[102:103]
	v_pk_fma_f32 v[100:101], v[176:177], v[100:101], v[106:107]
	v_pk_fma_f32 v[120:121], v[214:215], v[92:93], v[120:121]
	v_pk_fma_f32 v[100:101], v[178:179], v[98:99], v[100:101]
	s_waitcnt vmcnt(8)
	v_pk_fma_f32 v[102:103], v[180:181], v[98:99], v[102:103]
	v_pk_fma_f32 v[98:99], v[176:177], v[98:99], v[108:109]
	s_waitcnt vmcnt(7)
	v_pk_fma_f32 v[102:103], v[182:183], v[96:97], v[102:103]
	v_pk_fma_f32 v[100:101], v[180:181], v[96:97], v[100:101]
	v_pk_fma_f32 v[98:99], v[178:179], v[96:97], v[98:99]
	v_pk_fma_f32 v[96:97], v[176:177], v[96:97], v[110:111]
	s_waitcnt vmcnt(6)
	v_pk_fma_f32 v[102:103], v[184:185], v[94:95], v[102:103]
	v_pk_fma_f32 v[100:101], v[182:183], v[94:95], v[100:101]
	v_pk_fma_f32 v[98:99], v[180:181], v[94:95], v[98:99]
	v_pk_fma_f32 v[96:97], v[178:179], v[94:95], v[96:97]
	v_pk_fma_f32 v[94:95], v[176:177], v[94:95], v[112:113]
	v_pk_fma_f32 v[122:123], v[212:213], v[92:93], v[122:123]
	v_pk_fma_f32 v[124:125], v[210:211], v[92:93], v[124:125]
	v_pk_fma_f32 v[126:127], v[208:209], v[92:93], v[126:127]
	v_pk_fma_f32 v[128:129], v[206:207], v[92:93], v[128:129]
	v_pk_fma_f32 v[130:131], v[204:205], v[92:93], v[130:131]
	v_pk_fma_f32 v[132:133], v[202:203], v[92:93], v[132:133]
	v_pk_fma_f32 v[134:135], v[200:201], v[92:93], v[134:135]
	s_waitcnt vmcnt(5)
	v_pk_fma_f32 v[102:103], v[186:187], v[92:93], v[102:103]
	v_pk_fma_f32 v[100:101], v[184:185], v[92:93], v[100:101]
	v_pk_fma_f32 v[98:99], v[182:183], v[92:93], v[98:99]
	v_pk_fma_f32 v[96:97], v[180:181], v[92:93], v[96:97]
	v_pk_fma_f32 v[94:95], v[178:179], v[92:93], v[94:95]
	v_pk_fma_f32 v[92:93], v[176:177], v[92:93], v[114:115]
	v_pk_fma_f32 v[118:119], v[218:219], v[90:91], v[118:119]
	v_pk_fma_f32 v[120:121], v[216:217], v[90:91], v[120:121]
	v_pk_fma_f32 v[122:123], v[214:215], v[90:91], v[122:123]
	v_pk_fma_f32 v[124:125], v[212:213], v[90:91], v[124:125]
	v_pk_fma_f32 v[126:127], v[210:211], v[90:91], v[126:127]
	v_pk_fma_f32 v[128:129], v[208:209], v[90:91], v[128:129]
	v_pk_fma_f32 v[130:131], v[206:207], v[90:91], v[130:131]
	v_pk_fma_f32 v[132:133], v[204:205], v[90:91], v[132:133]
	v_pk_fma_f32 v[134:135], v[202:203], v[90:91], v[134:135]
	v_pk_fma_f32 v[136:137], v[200:201], v[90:91], v[136:137]
	s_waitcnt vmcnt(4)
	v_pk_fma_f32 v[102:103], v[188:189], v[90:91], v[102:103]
	v_pk_fma_f32 v[100:101], v[186:187], v[90:91], v[100:101]
	v_pk_fma_f32 v[98:99], v[184:185], v[90:91], v[98:99]
	v_pk_fma_f32 v[96:97], v[182:183], v[90:91], v[96:97]
	v_pk_fma_f32 v[94:95], v[180:181], v[90:91], v[94:95]
	v_pk_fma_f32 v[92:93], v[178:179], v[90:91], v[92:93]
	v_pk_fma_f32 v[90:91], v[176:177], v[90:91], v[116:117]
	v_pk_fma_f32 v[120:121], v[218:219], v[88:89], v[120:121]
	v_pk_fma_f32 v[122:123], v[216:217], v[88:89], v[122:123]
	v_pk_fma_f32 v[124:125], v[214:215], v[88:89], v[124:125]
	v_pk_fma_f32 v[126:127], v[212:213], v[88:89], v[126:127]
	v_pk_fma_f32 v[128:129], v[210:211], v[88:89], v[128:129]
	v_pk_fma_f32 v[130:131], v[208:209], v[88:89], v[130:131]
	v_pk_fma_f32 v[132:133], v[206:207], v[88:89], v[132:133]
	v_pk_fma_f32 v[134:135], v[204:205], v[88:89], v[134:135]
	v_pk_fma_f32 v[136:137], v[202:203], v[88:89], v[136:137]
	v_pk_fma_f32 v[138:139], v[200:201], v[88:89], v[138:139]
	s_waitcnt vmcnt(3)
; __device__ __forceinline__ void conv_unit(unsigned char* ws, LAS unsigned char* lds, int t0) {
;     ...
;     for (int j = 0; j < CONVK; ++j) {
;         const f32x2 w = *(const f32x2*)(conv_w + j * CONVW + c0);
; #pragma unroll
;         for (int t = 0; t < 32; ++t) { a0[t] += w[0] * y0[t + j]; a1[t] += w[1] * y1[t + j]; }
	v_pk_fma_f32 v[102:103], v[190:191], v[88:89], v[102:103]
	v_pk_fma_f32 v[100:101], v[188:189], v[88:89], v[100:101]
	v_pk_fma_f32 v[98:99], v[186:187], v[88:89], v[98:99]
	v_pk_fma_f32 v[96:97], v[184:185], v[88:89], v[96:97]
	v_pk_fma_f32 v[94:95], v[182:183], v[88:89], v[94:95]
	v_pk_fma_f32 v[92:93], v[180:181], v[88:89], v[92:93]
	v_pk_fma_f32 v[90:91], v[178:179], v[88:89], v[90:91]
	v_pk_fma_f32 v[88:89], v[176:177], v[88:89], v[118:119]
	v_pk_fma_f32 v[122:123], v[218:219], v[86:87], v[122:123]
	v_pk_fma_f32 v[124:125], v[216:217], v[86:87], v[124:125]
	v_pk_fma_f32 v[126:127], v[214:215], v[86:87], v[126:127]
	v_pk_fma_f32 v[128:129], v[212:213], v[86:87], v[128:129]
	v_pk_fma_f32 v[130:131], v[210:211], v[86:87], v[130:131]
	v_pk_fma_f32 v[132:133], v[208:209], v[86:87], v[132:133]
	v_pk_fma_f32 v[134:135], v[206:207], v[86:87], v[134:135]
	v_pk_fma_f32 v[136:137], v[204:205], v[86:87], v[136:137]
	v_pk_fma_f32 v[138:139], v[202:203], v[86:87], v[138:139]
	v_pk_fma_f32 v[140:141], v[200:201], v[86:87], v[140:141]
	s_waitcnt vmcnt(2)
	v_pk_fma_f32 v[102:103], v[192:193], v[86:87], v[102:103]
	v_pk_fma_f32 v[100:101], v[190:191], v[86:87], v[100:101]
	v_pk_fma_f32 v[98:99], v[188:189], v[86:87], v[98:99]
	v_pk_fma_f32 v[96:97], v[186:187], v[86:87], v[96:97]
	v_pk_fma_f32 v[94:95], v[184:185], v[86:87], v[94:95]
	v_pk_fma_f32 v[92:93], v[182:183], v[86:87], v[92:93]
	v_pk_fma_f32 v[90:91], v[180:181], v[86:87], v[90:91]
	v_pk_fma_f32 v[88:89], v[178:179], v[86:87], v[88:89]
	v_pk_fma_f32 v[86:87], v[176:177], v[86:87], v[120:121]
	v_pk_fma_f32 v[124:125], v[218:219], v[84:85], v[124:125]
	v_pk_fma_f32 v[126:127], v[216:217], v[84:85], v[126:127]
	v_pk_fma_f32 v[128:129], v[214:215], v[84:85], v[128:129]
	v_pk_fma_f32 v[130:131], v[212:213], v[84:85], v[130:131]
	v_pk_fma_f32 v[132:133], v[210:211], v[84:85], v[132:133]
	v_pk_fma_f32 v[134:135], v[208:209], v[84:85], v[134:135]
	v_pk_fma_f32 v[136:137], v[206:207], v[84:85], v[136:137]
	v_pk_fma_f32 v[138:139], v[204:205], v[84:85], v[138:139]
	v_pk_fma_f32 v[140:141], v[202:203], v[84:85], v[140:141]
	v_pk_fma_f32 v[142:143], v[200:201], v[84:85], v[142:143]
	s_waitcnt vmcnt(1)
	v_pk_fma_f32 v[102:103], v[194:195], v[84:85], v[102:103]
	v_pk_fma_f32 v[100:101], v[192:193], v[84:85], v[100:101]
	v_pk_fma_f32 v[98:99], v[190:191], v[84:85], v[98:99]
	v_pk_fma_f32 v[96:97], v[188:189], v[84:85], v[96:97]
	v_pk_fma_f32 v[94:95], v[186:187], v[84:85], v[94:95]
	v_pk_fma_f32 v[92:93], v[184:185], v[84:85], v[92:93]
	v_pk_fma_f32 v[90:91], v[182:183], v[84:85], v[90:91]
	v_pk_fma_f32 v[88:89], v[180:181], v[84:85], v[88:89]
	v_pk_fma_f32 v[86:87], v[178:179], v[84:85], v[86:87]
	v_pk_fma_f32 v[84:85], v[176:177], v[84:85], v[122:123]
	v_pk_fma_f32 v[126:127], v[218:219], v[82:83], v[126:127]
	v_pk_fma_f32 v[128:129], v[216:217], v[82:83], v[128:129]
	v_pk_fma_f32 v[130:131], v[214:215], v[82:83], v[130:131]
	v_pk_fma_f32 v[132:133], v[212:213], v[82:83], v[132:133]
	v_pk_fma_f32 v[134:135], v[210:211], v[82:83], v[134:135]
	v_pk_fma_f32 v[136:137], v[208:209], v[82:83], v[136:137]
	v_pk_fma_f32 v[138:139], v[206:207], v[82:83], v[138:139]
	v_pk_fma_f32 v[140:141], v[204:205], v[82:83], v[140:141]
	v_pk_fma_f32 v[142:143], v[202:203], v[82:83], v[142:143]
	v_pk_fma_f32 v[144:145], v[200:201], v[82:83], v[144:145]
	s_waitcnt vmcnt(0)
	v_pk_fma_f32 v[102:103], v[198:199], v[82:83], v[102:103]
	v_pk_fma_f32 v[100:101], v[194:195], v[82:83], v[100:101]
	v_pk_fma_f32 v[98:99], v[192:193], v[82:83], v[98:99]
	v_pk_fma_f32 v[96:97], v[190:191], v[82:83], v[96:97]
	v_pk_fma_f32 v[94:95], v[188:189], v[82:83], v[94:95]
	v_pk_fma_f32 v[92:93], v[186:187], v[82:83], v[92:93]
	v_pk_fma_f32 v[90:91], v[184:185], v[82:83], v[90:91]
	v_pk_fma_f32 v[88:89], v[182:183], v[82:83], v[88:89]
	v_pk_fma_f32 v[86:87], v[180:181], v[82:83], v[86:87]
	v_pk_fma_f32 v[84:85], v[178:179], v[82:83], v[84:85]
	v_pk_fma_f32 v[82:83], v[176:177], v[82:83], v[124:125]
	v_pk_fma_f32 v[128:129], v[218:219], v[78:79], v[128:129]
	v_pk_fma_f32 v[82:83], v[178:179], v[78:79], v[82:83]
	v_pk_fma_f32 v[130:131], v[216:217], v[78:79], v[130:131]
	v_pk_fma_f32 v[82:83], v[180:181], v[76:77], v[82:83]
	v_pk_fma_f32 v[130:131], v[218:219], v[76:77], v[130:131]
	v_pk_fma_f32 v[82:83], v[182:183], v[74:75], v[82:83]
	v_pk_fma_f32 v[132:133], v[214:215], v[78:79], v[132:133]
	v_pk_fma_f32 v[82:83], v[184:185], v[72:73], v[82:83]
	v_pk_fma_f32 v[132:133], v[216:217], v[76:77], v[132:133]
	v_pk_fma_f32 v[82:83], v[186:187], v[70:71], v[82:83]
	v_pk_fma_f32 v[132:133], v[218:219], v[74:75], v[132:133]
	v_pk_fma_f32 v[82:83], v[188:189], v[68:69], v[82:83]
	v_pk_fma_f32 v[134:135], v[212:213], v[78:79], v[134:135]
	v_pk_fma_f32 v[82:83], v[190:191], v[66:67], v[82:83]
	v_pk_fma_f32 v[134:135], v[214:215], v[76:77], v[134:135]
	v_pk_fma_f32 v[82:83], v[192:193], v[64:65], v[82:83]
	v_pk_fma_f32 v[134:135], v[216:217], v[74:75], v[134:135]
	v_pk_fma_f32 v[82:83], v[194:195], v[62:63], v[82:83]
	v_pk_fma_f32 v[134:135], v[218:219], v[72:73], v[134:135]
	v_pk_fma_f32 v[108:109], v[198:199], v[60:61], v[82:83]
	v_pk_fma_f32 v[82:83], v[176:177], v[78:79], v[126:127]
	v_pk_fma_f32 v[136:137], v[210:211], v[78:79], v[136:137]
	v_pk_fma_f32 v[82:83], v[178:179], v[76:77], v[82:83]
	v_pk_fma_f32 v[136:137], v[212:213], v[76:77], v[136:137]
	v_pk_fma_f32 v[82:83], v[180:181], v[74:75], v[82:83]
	v_pk_fma_f32 v[136:137], v[214:215], v[74:75], v[136:137]
	v_pk_fma_f32 v[82:83], v[182:183], v[72:73], v[82:83]
	v_pk_fma_f32 v[136:137], v[216:217], v[72:73], v[136:137]
	v_pk_fma_f32 v[82:83], v[184:185], v[70:71], v[82:83]
; __device__ __forceinline__ void conv_unit(unsigned char* ws, LAS unsigned char* lds, int t0) {
;     ...
;     for (int j = 0; j < CONVK; ++j) {
;         const f32x2 w = *(const f32x2*)(conv_w + j * CONVW + c0);
; #pragma unroll
;         for (int t = 0; t < 32; ++t) { a0[t] += w[0] * y0[t + j]; a1[t] += w[1] * y1[t + j]; }
	v_pk_fma_f32 v[136:137], v[218:219], v[70:71], v[136:137]
	v_pk_fma_f32 v[82:83], v[186:187], v[68:69], v[82:83]
	v_pk_fma_f32 v[138:139], v[208:209], v[78:79], v[138:139]
	v_pk_fma_f32 v[82:83], v[188:189], v[66:67], v[82:83]
	v_pk_fma_f32 v[138:139], v[210:211], v[76:77], v[138:139]
	v_pk_fma_f32 v[82:83], v[190:191], v[64:65], v[82:83]
	v_pk_fma_f32 v[138:139], v[212:213], v[74:75], v[138:139]
	v_pk_fma_f32 v[82:83], v[192:193], v[62:63], v[82:83]
	v_pk_fma_f32 v[138:139], v[214:215], v[72:73], v[138:139]
	v_pk_fma_f32 v[82:83], v[194:195], v[60:61], v[82:83]
	v_pk_fma_f32 v[138:139], v[216:217], v[70:71], v[138:139]
	v_pk_fma_f32 v[110:111], v[198:199], v[56:57], v[82:83]
	v_pk_fma_f32 v[82:83], v[176:177], v[76:77], v[128:129]
	v_pk_fma_f32 v[138:139], v[218:219], v[68:69], v[138:139]
	v_pk_fma_f32 v[82:83], v[178:179], v[74:75], v[82:83]
	v_pk_fma_f32 v[140:141], v[206:207], v[78:79], v[140:141]
	v_pk_fma_f32 v[82:83], v[180:181], v[72:73], v[82:83]
	v_pk_fma_f32 v[140:141], v[208:209], v[76:77], v[140:141]
	v_pk_fma_f32 v[82:83], v[182:183], v[70:71], v[82:83]
	v_pk_fma_f32 v[140:141], v[210:211], v[74:75], v[140:141]
	v_pk_fma_f32 v[82:83], v[184:185], v[68:69], v[82:83]
	v_pk_fma_f32 v[140:141], v[212:213], v[72:73], v[140:141]
	v_pk_fma_f32 v[82:83], v[186:187], v[66:67], v[82:83]
	v_pk_fma_f32 v[140:141], v[214:215], v[70:71], v[140:141]
	v_pk_fma_f32 v[82:83], v[188:189], v[64:65], v[82:83]
	v_pk_fma_f32 v[140:141], v[216:217], v[68:69], v[140:141]
	v_pk_fma_f32 v[82:83], v[190:191], v[62:63], v[82:83]
	v_pk_fma_f32 v[140:141], v[218:219], v[66:67], v[140:141]
	v_pk_fma_f32 v[82:83], v[192:193], v[60:61], v[82:83]
	v_pk_fma_f32 v[142:143], v[204:205], v[78:79], v[142:143]
	v_pk_fma_f32 v[82:83], v[194:195], v[56:57], v[82:83]
	v_pk_fma_f32 v[142:143], v[206:207], v[76:77], v[142:143]
	v_pk_fma_f32 v[112:113], v[198:199], v[54:55], v[82:83]
	v_pk_fma_f32 v[82:83], v[176:177], v[74:75], v[130:131]
	v_pk_fma_f32 v[142:143], v[208:209], v[74:75], v[142:143]
	v_pk_fma_f32 v[82:83], v[178:179], v[72:73], v[82:83]
	v_pk_fma_f32 v[142:143], v[210:211], v[72:73], v[142:143]
	v_pk_fma_f32 v[82:83], v[180:181], v[70:71], v[82:83]
	v_pk_fma_f32 v[142:143], v[212:213], v[70:71], v[142:143]
	v_pk_fma_f32 v[82:83], v[182:183], v[68:69], v[82:83]
	v_pk_fma_f32 v[142:143], v[214:215], v[68:69], v[142:143]
	v_pk_fma_f32 v[82:83], v[184:185], v[66:67], v[82:83]
	v_pk_fma_f32 v[142:143], v[216:217], v[66:67], v[142:143]
	v_pk_fma_f32 v[82:83], v[186:187], v[64:65], v[82:83]
	v_pk_fma_f32 v[142:143], v[218:219], v[64:65], v[142:143]
	v_pk_fma_f32 v[82:83], v[188:189], v[62:63], v[82:83]
	v_pk_fma_f32 v[144:145], v[202:203], v[78:79], v[144:145]
	v_pk_fma_f32 v[82:83], v[190:191], v[60:61], v[82:83]
	v_pk_fma_f32 v[144:145], v[204:205], v[76:77], v[144:145]
	v_pk_fma_f32 v[82:83], v[192:193], v[56:57], v[82:83]
	v_pk_fma_f32 v[144:145], v[206:207], v[74:75], v[144:145]
	v_pk_fma_f32 v[82:83], v[194:195], v[54:55], v[82:83]
	v_pk_fma_f32 v[144:145], v[208:209], v[72:73], v[144:145]
	v_pk_fma_f32 v[114:115], v[198:199], v[52:53], v[82:83]
	v_pk_fma_f32 v[82:83], v[176:177], v[72:73], v[132:133]
	v_pk_fma_f32 v[144:145], v[210:211], v[70:71], v[144:145]
	v_pk_fma_f32 v[82:83], v[178:179], v[70:71], v[82:83]
	v_pk_fma_f32 v[144:145], v[212:213], v[68:69], v[144:145]
	v_pk_fma_f32 v[82:83], v[180:181], v[68:69], v[82:83]
	v_pk_fma_f32 v[144:145], v[214:215], v[66:67], v[144:145]
	v_pk_fma_f32 v[82:83], v[182:183], v[66:67], v[82:83]
	v_pk_fma_f32 v[144:145], v[216:217], v[64:65], v[144:145]
	v_pk_fma_f32 v[82:83], v[184:185], v[64:65], v[82:83]
	v_pk_fma_f32 v[144:145], v[218:219], v[62:63], v[144:145]
	v_pk_fma_f32 v[82:83], v[186:187], v[62:63], v[82:83]
	v_pk_fma_f32 v[146:147], v[200:201], v[78:79], v[146:147]
	v_pk_fma_f32 v[82:83], v[188:189], v[60:61], v[82:83]
	v_pk_fma_f32 v[146:147], v[202:203], v[76:77], v[146:147]
	v_pk_fma_f32 v[82:83], v[190:191], v[56:57], v[82:83]
	v_pk_fma_f32 v[146:147], v[204:205], v[74:75], v[146:147]
	v_pk_fma_f32 v[82:83], v[192:193], v[54:55], v[82:83]
	v_pk_fma_f32 v[146:147], v[206:207], v[72:73], v[146:147]
	v_pk_fma_f32 v[82:83], v[194:195], v[52:53], v[82:83]
	v_pk_fma_f32 v[146:147], v[208:209], v[70:71], v[146:147]
	v_pk_fma_f32 v[116:117], v[198:199], v[50:51], v[82:83]
	v_pk_fma_f32 v[82:83], v[176:177], v[70:71], v[134:135]
	v_pk_fma_f32 v[146:147], v[210:211], v[68:69], v[146:147]
	v_pk_fma_f32 v[82:83], v[178:179], v[68:69], v[82:83]
	v_pk_fma_f32 v[146:147], v[212:213], v[66:67], v[146:147]
	v_pk_fma_f32 v[82:83], v[180:181], v[66:67], v[82:83]
	v_pk_fma_f32 v[146:147], v[214:215], v[64:65], v[146:147]
	v_pk_fma_f32 v[82:83], v[182:183], v[64:65], v[82:83]
	v_pk_fma_f32 v[146:147], v[216:217], v[62:63], v[146:147]
	v_pk_fma_f32 v[82:83], v[184:185], v[62:63], v[82:83]
	v_pk_fma_f32 v[146:147], v[218:219], v[60:61], v[146:147]
	v_pk_fma_f32 v[82:83], v[186:187], v[60:61], v[82:83]
	v_pk_fma_f32 v[148:149], v[200:201], v[76:77], v[148:149]
	v_pk_fma_f32 v[82:83], v[188:189], v[56:57], v[82:83]
	v_pk_fma_f32 v[148:149], v[202:203], v[74:75], v[148:149]
	v_pk_fma_f32 v[82:83], v[190:191], v[54:55], v[82:83]
	v_pk_fma_f32 v[148:149], v[204:205], v[72:73], v[148:149]
	v_pk_fma_f32 v[82:83], v[192:193], v[52:53], v[82:83]
	v_pk_fma_f32 v[148:149], v[206:207], v[70:71], v[148:149]
	v_pk_fma_f32 v[82:83], v[194:195], v[50:51], v[82:83]
	v_pk_fma_f32 v[148:149], v[208:209], v[68:69], v[148:149]
	v_pk_fma_f32 v[118:119], v[198:199], v[48:49], v[82:83]
	v_pk_fma_f32 v[82:83], v[176:177], v[68:69], v[136:137]
	v_pk_fma_f32 v[148:149], v[210:211], v[66:67], v[148:149]
	v_pk_fma_f32 v[82:83], v[178:179], v[66:67], v[82:83]
; __device__ __forceinline__ void conv_unit(unsigned char* ws, LAS unsigned char* lds, int t0) {
;     ...
;     for (int j = 0; j < CONVK; ++j) {
;         const f32x2 w = *(const f32x2*)(conv_w + j * CONVW + c0);
; #pragma unroll
;         for (int t = 0; t < 32; ++t) { a0[t] += w[0] * y0[t + j]; a1[t] += w[1] * y1[t + j]; }
	v_pk_fma_f32 v[148:149], v[212:213], v[64:65], v[148:149]
	v_pk_fma_f32 v[82:83], v[180:181], v[64:65], v[82:83]
	v_pk_fma_f32 v[148:149], v[214:215], v[62:63], v[148:149]
	v_pk_fma_f32 v[82:83], v[182:183], v[62:63], v[82:83]
	v_pk_fma_f32 v[148:149], v[216:217], v[60:61], v[148:149]
	v_pk_fma_f32 v[82:83], v[184:185], v[60:61], v[82:83]
	v_pk_fma_f32 v[148:149], v[218:219], v[56:57], v[148:149]
	v_pk_fma_f32 v[82:83], v[186:187], v[56:57], v[82:83]
	v_pk_fma_f32 v[150:151], v[200:201], v[74:75], v[150:151]
	v_pk_fma_f32 v[82:83], v[188:189], v[54:55], v[82:83]
	v_pk_fma_f32 v[150:151], v[202:203], v[72:73], v[150:151]
	v_pk_fma_f32 v[82:83], v[190:191], v[52:53], v[82:83]
	v_pk_fma_f32 v[150:151], v[204:205], v[70:71], v[150:151]
	v_pk_fma_f32 v[82:83], v[192:193], v[50:51], v[82:83]
	v_pk_fma_f32 v[150:151], v[206:207], v[68:69], v[150:151]
	v_pk_fma_f32 v[82:83], v[194:195], v[48:49], v[82:83]
	v_pk_fma_f32 v[150:151], v[208:209], v[66:67], v[150:151]
	v_pk_fma_f32 v[120:121], v[198:199], v[46:47], v[82:83]
	v_pk_fma_f32 v[82:83], v[176:177], v[66:67], v[138:139]
	v_pk_fma_f32 v[150:151], v[210:211], v[64:65], v[150:151]
	v_pk_fma_f32 v[82:83], v[178:179], v[64:65], v[82:83]
	v_pk_fma_f32 v[150:151], v[212:213], v[62:63], v[150:151]
	v_pk_fma_f32 v[82:83], v[180:181], v[62:63], v[82:83]
	v_pk_fma_f32 v[150:151], v[214:215], v[60:61], v[150:151]
	v_pk_fma_f32 v[82:83], v[182:183], v[60:61], v[82:83]
	v_pk_fma_f32 v[150:151], v[216:217], v[56:57], v[150:151]
	v_pk_fma_f32 v[82:83], v[184:185], v[56:57], v[82:83]
	v_pk_fma_f32 v[150:151], v[218:219], v[54:55], v[150:151]
	v_pk_fma_f32 v[82:83], v[186:187], v[54:55], v[82:83]
	v_pk_fma_f32 v[152:153], v[200:201], v[72:73], v[152:153]
	v_pk_fma_f32 v[82:83], v[188:189], v[52:53], v[82:83]
	v_pk_fma_f32 v[152:153], v[202:203], v[70:71], v[152:153]
	v_pk_fma_f32 v[82:83], v[190:191], v[50:51], v[82:83]
	v_pk_fma_f32 v[152:153], v[204:205], v[68:69], v[152:153]
	v_pk_fma_f32 v[82:83], v[192:193], v[48:49], v[82:83]
	v_pk_fma_f32 v[152:153], v[206:207], v[66:67], v[152:153]
	v_pk_fma_f32 v[82:83], v[194:195], v[46:47], v[82:83]
	v_pk_fma_f32 v[152:153], v[208:209], v[64:65], v[152:153]
	v_pk_fma_f32 v[122:123], v[198:199], v[44:45], v[82:83]
	v_pk_fma_f32 v[82:83], v[176:177], v[64:65], v[140:141]
	v_pk_fma_f32 v[152:153], v[210:211], v[62:63], v[152:153]
	v_pk_fma_f32 v[82:83], v[178:179], v[62:63], v[82:83]
	v_pk_fma_f32 v[152:153], v[212:213], v[60:61], v[152:153]
	v_pk_fma_f32 v[82:83], v[180:181], v[60:61], v[82:83]
	v_pk_fma_f32 v[152:153], v[214:215], v[56:57], v[152:153]
	v_pk_fma_f32 v[82:83], v[182:183], v[56:57], v[82:83]
	v_pk_fma_f32 v[152:153], v[216:217], v[54:55], v[152:153]
	v_pk_fma_f32 v[82:83], v[184:185], v[54:55], v[82:83]
	v_pk_fma_f32 v[152:153], v[218:219], v[52:53], v[152:153]
	v_pk_fma_f32 v[82:83], v[186:187], v[52:53], v[82:83]
	v_pk_fma_f32 v[154:155], v[200:201], v[70:71], v[154:155]
	v_pk_fma_f32 v[82:83], v[188:189], v[50:51], v[82:83]
	v_pk_fma_f32 v[154:155], v[202:203], v[68:69], v[154:155]
	v_pk_fma_f32 v[82:83], v[190:191], v[48:49], v[82:83]
	v_pk_fma_f32 v[154:155], v[204:205], v[66:67], v[154:155]
	v_pk_fma_f32 v[82:83], v[192:193], v[46:47], v[82:83]
	v_pk_fma_f32 v[154:155], v[206:207], v[64:65], v[154:155]
	v_pk_fma_f32 v[82:83], v[194:195], v[44:45], v[82:83]
	v_pk_fma_f32 v[154:155], v[208:209], v[62:63], v[154:155]
	v_pk_fma_f32 v[124:125], v[198:199], v[42:43], v[82:83]
	v_pk_fma_f32 v[82:83], v[176:177], v[62:63], v[142:143]
	v_pk_fma_f32 v[154:155], v[210:211], v[60:61], v[154:155]
	v_pk_fma_f32 v[82:83], v[178:179], v[60:61], v[82:83]
	v_pk_fma_f32 v[154:155], v[212:213], v[56:57], v[154:155]
	v_pk_fma_f32 v[82:83], v[180:181], v[56:57], v[82:83]
	v_pk_fma_f32 v[154:155], v[214:215], v[54:55], v[154:155]
	v_pk_fma_f32 v[82:83], v[182:183], v[54:55], v[82:83]
	v_pk_fma_f32 v[154:155], v[216:217], v[52:53], v[154:155]
	v_pk_fma_f32 v[82:83], v[184:185], v[52:53], v[82:83]
	v_pk_fma_f32 v[154:155], v[218:219], v[50:51], v[154:155]
	v_pk_fma_f32 v[82:83], v[186:187], v[50:51], v[82:83]
	v_pk_fma_f32 v[156:157], v[200:201], v[68:69], v[156:157]
	v_pk_fma_f32 v[82:83], v[188:189], v[48:49], v[82:83]
	v_pk_fma_f32 v[156:157], v[202:203], v[66:67], v[156:157]
	v_pk_fma_f32 v[82:83], v[190:191], v[46:47], v[82:83]
	v_pk_fma_f32 v[156:157], v[204:205], v[64:65], v[156:157]
	v_pk_fma_f32 v[82:83], v[192:193], v[44:45], v[82:83]
	v_pk_fma_f32 v[156:157], v[206:207], v[62:63], v[156:157]
	v_pk_fma_f32 v[82:83], v[194:195], v[42:43], v[82:83]
	v_pk_fma_f32 v[156:157], v[208:209], v[60:61], v[156:157]
	v_pk_fma_f32 v[126:127], v[198:199], v[40:41], v[82:83]
	v_pk_fma_f32 v[82:83], v[176:177], v[60:61], v[144:145]
	v_pk_fma_f32 v[156:157], v[210:211], v[56:57], v[156:157]
	v_pk_fma_f32 v[82:83], v[178:179], v[56:57], v[82:83]
	v_pk_fma_f32 v[156:157], v[212:213], v[54:55], v[156:157]
	v_pk_fma_f32 v[82:83], v[180:181], v[54:55], v[82:83]
	v_pk_fma_f32 v[156:157], v[214:215], v[52:53], v[156:157]
	v_pk_fma_f32 v[82:83], v[182:183], v[52:53], v[82:83]
	v_pk_fma_f32 v[156:157], v[216:217], v[50:51], v[156:157]
	v_pk_fma_f32 v[82:83], v[184:185], v[50:51], v[82:83]
	v_pk_fma_f32 v[156:157], v[218:219], v[48:49], v[156:157]
	v_pk_fma_f32 v[82:83], v[186:187], v[48:49], v[82:83]
	v_pk_fma_f32 v[158:159], v[200:201], v[66:67], v[158:159]
	v_pk_fma_f32 v[82:83], v[188:189], v[46:47], v[82:83]
	v_pk_fma_f32 v[158:159], v[202:203], v[64:65], v[158:159]
	v_pk_fma_f32 v[82:83], v[190:191], v[44:45], v[82:83]
	v_pk_fma_f32 v[158:159], v[204:205], v[62:63], v[158:159]
	v_pk_fma_f32 v[82:83], v[192:193], v[42:43], v[82:83]
	v_pk_fma_f32 v[158:159], v[206:207], v[60:61], v[158:159]
; __device__ __forceinline__ void conv_unit(unsigned char* ws, LAS unsigned char* lds, int t0) {
;     ...
;     for (int j = 0; j < CONVK; ++j) {
;         const f32x2 w = *(const f32x2*)(conv_w + j * CONVW + c0);
; #pragma unroll
;         for (int t = 0; t < 32; ++t) { a0[t] += w[0] * y0[t + j]; a1[t] += w[1] * y1[t + j]; }
	v_pk_fma_f32 v[82:83], v[194:195], v[40:41], v[82:83]
	v_pk_fma_f32 v[158:159], v[208:209], v[56:57], v[158:159]
	v_pk_fma_f32 v[128:129], v[198:199], v[38:39], v[82:83]
	v_pk_fma_f32 v[82:83], v[176:177], v[56:57], v[146:147]
	v_pk_fma_f32 v[158:159], v[210:211], v[54:55], v[158:159]
	v_pk_fma_f32 v[82:83], v[178:179], v[54:55], v[82:83]
	v_pk_fma_f32 v[158:159], v[212:213], v[52:53], v[158:159]
	v_pk_fma_f32 v[82:83], v[180:181], v[52:53], v[82:83]
	v_pk_fma_f32 v[158:159], v[214:215], v[50:51], v[158:159]
	v_pk_fma_f32 v[82:83], v[182:183], v[50:51], v[82:83]
	v_pk_fma_f32 v[158:159], v[216:217], v[48:49], v[158:159]
	v_pk_fma_f32 v[82:83], v[184:185], v[48:49], v[82:83]
	v_pk_fma_f32 v[158:159], v[218:219], v[46:47], v[158:159]
	v_pk_fma_f32 v[82:83], v[186:187], v[46:47], v[82:83]
	v_pk_fma_f32 v[168:169], v[200:201], v[64:65], v[168:169]
	v_pk_fma_f32 v[82:83], v[188:189], v[44:45], v[82:83]
	v_pk_fma_f32 v[168:169], v[202:203], v[62:63], v[168:169]
	v_pk_fma_f32 v[82:83], v[190:191], v[42:43], v[82:83]
	v_pk_fma_f32 v[168:169], v[204:205], v[60:61], v[168:169]
	v_pk_fma_f32 v[82:83], v[192:193], v[40:41], v[82:83]
	v_pk_fma_f32 v[168:169], v[206:207], v[56:57], v[168:169]
	v_pk_fma_f32 v[82:83], v[194:195], v[38:39], v[82:83]
	v_pk_fma_f32 v[168:169], v[208:209], v[54:55], v[168:169]
	v_pk_fma_f32 v[130:131], v[198:199], v[36:37], v[82:83]
	v_pk_fma_f32 v[82:83], v[176:177], v[54:55], v[148:149]
	v_pk_fma_f32 v[168:169], v[210:211], v[52:53], v[168:169]
	v_pk_fma_f32 v[82:83], v[178:179], v[52:53], v[82:83]
	v_pk_fma_f32 v[168:169], v[212:213], v[50:51], v[168:169]
	v_pk_fma_f32 v[82:83], v[180:181], v[50:51], v[82:83]
	v_pk_fma_f32 v[168:169], v[214:215], v[48:49], v[168:169]
	v_pk_fma_f32 v[82:83], v[182:183], v[48:49], v[82:83]
	v_pk_fma_f32 v[168:169], v[216:217], v[46:47], v[168:169]
	v_pk_fma_f32 v[82:83], v[184:185], v[46:47], v[82:83]
	v_pk_fma_f32 v[168:169], v[218:219], v[44:45], v[168:169]
	v_pk_fma_f32 v[82:83], v[186:187], v[44:45], v[82:83]
	v_pk_fma_f32 v[170:171], v[200:201], v[62:63], v[170:171]
	v_pk_fma_f32 v[82:83], v[188:189], v[42:43], v[82:83]
	v_pk_fma_f32 v[170:171], v[202:203], v[60:61], v[170:171]
	v_pk_fma_f32 v[82:83], v[190:191], v[40:41], v[82:83]
	v_pk_fma_f32 v[170:171], v[204:205], v[56:57], v[170:171]
	v_pk_fma_f32 v[82:83], v[192:193], v[38:39], v[82:83]
	v_pk_fma_f32 v[170:171], v[206:207], v[54:55], v[170:171]
	v_pk_fma_f32 v[82:83], v[194:195], v[36:37], v[82:83]
	v_pk_fma_f32 v[170:171], v[208:209], v[52:53], v[170:171]
	v_pk_fma_f32 v[132:133], v[198:199], v[34:35], v[82:83]
	v_pk_fma_f32 v[82:83], v[176:177], v[52:53], v[150:151]
	v_pk_fma_f32 v[170:171], v[210:211], v[50:51], v[170:171]
	v_pk_fma_f32 v[82:83], v[178:179], v[50:51], v[82:83]
	v_pk_fma_f32 v[170:171], v[212:213], v[48:49], v[170:171]
	v_pk_fma_f32 v[82:83], v[180:181], v[48:49], v[82:83]
	v_pk_fma_f32 v[170:171], v[214:215], v[46:47], v[170:171]
	v_pk_fma_f32 v[82:83], v[182:183], v[46:47], v[82:83]
	v_pk_fma_f32 v[170:171], v[216:217], v[44:45], v[170:171]
	v_pk_fma_f32 v[82:83], v[184:185], v[44:45], v[82:83]
	v_pk_fma_f32 v[170:171], v[218:219], v[42:43], v[170:171]
	v_pk_fma_f32 v[82:83], v[186:187], v[42:43], v[82:83]
	v_pk_fma_f32 v[172:173], v[200:201], v[60:61], v[172:173]
	v_pk_fma_f32 v[82:83], v[188:189], v[40:41], v[82:83]
	v_pk_fma_f32 v[172:173], v[202:203], v[56:57], v[172:173]
	v_pk_fma_f32 v[82:83], v[190:191], v[38:39], v[82:83]
	v_pk_fma_f32 v[172:173], v[204:205], v[54:55], v[172:173]
	v_pk_fma_f32 v[82:83], v[192:193], v[36:37], v[82:83]
	v_pk_fma_f32 v[172:173], v[206:207], v[52:53], v[172:173]
	v_pk_fma_f32 v[82:83], v[194:195], v[34:35], v[82:83]
	v_pk_fma_f32 v[172:173], v[208:209], v[50:51], v[172:173]
	v_pk_fma_f32 v[134:135], v[198:199], v[32:33], v[82:83]
	v_pk_fma_f32 v[82:83], v[176:177], v[50:51], v[152:153]
	v_pk_fma_f32 v[172:173], v[210:211], v[48:49], v[172:173]
	v_pk_fma_f32 v[82:83], v[178:179], v[48:49], v[82:83]
	v_pk_fma_f32 v[172:173], v[212:213], v[46:47], v[172:173]
	v_pk_fma_f32 v[82:83], v[180:181], v[46:47], v[82:83]
	v_pk_fma_f32 v[172:173], v[214:215], v[44:45], v[172:173]
	v_pk_fma_f32 v[82:83], v[182:183], v[44:45], v[82:83]
	v_pk_fma_f32 v[172:173], v[216:217], v[42:43], v[172:173]
	v_pk_fma_f32 v[82:83], v[184:185], v[42:43], v[82:83]
	v_pk_fma_f32 v[172:173], v[218:219], v[40:41], v[172:173]
	v_pk_fma_f32 v[82:83], v[186:187], v[40:41], v[82:83]
	v_pk_fma_f32 v[174:175], v[200:201], v[56:57], v[174:175]
	v_pk_fma_f32 v[82:83], v[188:189], v[38:39], v[82:83]
	v_pk_fma_f32 v[174:175], v[202:203], v[54:55], v[174:175]
	v_pk_fma_f32 v[82:83], v[190:191], v[36:37], v[82:83]
	v_pk_fma_f32 v[174:175], v[204:205], v[52:53], v[174:175]
	v_pk_fma_f32 v[82:83], v[192:193], v[34:35], v[82:83]
	v_pk_fma_f32 v[174:175], v[206:207], v[50:51], v[174:175]
	v_pk_fma_f32 v[82:83], v[194:195], v[32:33], v[82:83]
	v_pk_fma_f32 v[174:175], v[208:209], v[48:49], v[174:175]
	v_pk_fma_f32 v[136:137], v[198:199], v[30:31], v[82:83]
	v_pk_fma_f32 v[82:83], v[176:177], v[48:49], v[154:155]
	v_pk_fma_f32 v[174:175], v[210:211], v[46:47], v[174:175]
	v_pk_fma_f32 v[82:83], v[178:179], v[46:47], v[82:83]
	v_pk_fma_f32 v[174:175], v[212:213], v[44:45], v[174:175]
	v_pk_fma_f32 v[82:83], v[180:181], v[44:45], v[82:83]
	v_pk_fma_f32 v[174:175], v[214:215], v[42:43], v[174:175]
	v_pk_fma_f32 v[82:83], v[182:183], v[42:43], v[82:83]
	v_pk_fma_f32 v[174:175], v[216:217], v[40:41], v[174:175]
	v_pk_fma_f32 v[82:83], v[184:185], v[40:41], v[82:83]
	v_pk_fma_f32 v[174:175], v[218:219], v[38:39], v[174:175]
	v_pk_fma_f32 v[82:83], v[186:187], v[38:39], v[82:83]
	s_mov_b32 s19, 0x1c000
; __device__ __forceinline__ void conv_unit(unsigned char* ws, LAS unsigned char* lds, int t0) {
;     ...
;     for (int j = 0; j < CONVK; ++j) {
;         const f32x2 w = *(const f32x2*)(conv_w + j * CONVW + c0);
; #pragma unroll
;         for (int t = 0; t < 32; ++t) { a0[t] += w[0] * y0[t + j]; a1[t] += w[1] * y1[t + j]; }
	v_pk_fma_f32 v[82:83], v[188:189], v[36:37], v[82:83]
	global_load_dwordx2 v[152:153], v[196:197], off
	v_pk_fma_f32 v[82:83], v[190:191], v[34:35], v[82:83]
	v_pk_fma_f32 v[86:87], v[182:183], v[78:79], v[86:87]
	v_pk_fma_f32 v[82:83], v[192:193], v[32:33], v[82:83]
	v_pk_fma_f32 v[84:85], v[180:181], v[78:79], v[84:85]
	v_pk_fma_f32 v[82:83], v[194:195], v[30:31], v[82:83]
	v_pk_fma_f32 v[86:87], v[184:185], v[76:77], v[86:87]
	v_pk_fma_f32 v[138:139], v[198:199], v[28:29], v[82:83]
	v_pk_fma_f32 v[82:83], v[176:177], v[46:47], v[156:157]
	v_pk_fma_f32 v[84:85], v[182:183], v[76:77], v[84:85]
	v_pk_fma_f32 v[82:83], v[178:179], v[44:45], v[82:83]
	v_pk_fma_f32 v[86:87], v[186:187], v[74:75], v[86:87]
	v_pk_fma_f32 v[82:83], v[180:181], v[42:43], v[82:83]
	v_pk_fma_f32 v[84:85], v[184:185], v[74:75], v[84:85]
	v_pk_fma_f32 v[82:83], v[182:183], v[40:41], v[82:83]
	v_pk_fma_f32 v[100:101], v[198:199], v[78:79], v[100:101]
	v_pk_fma_f32 v[82:83], v[184:185], v[38:39], v[82:83]
	v_pk_fma_f32 v[98:99], v[194:195], v[78:79], v[98:99]
	v_pk_fma_f32 v[82:83], v[186:187], v[36:37], v[82:83]
	v_pk_fma_f32 v[96:97], v[192:193], v[78:79], v[96:97]
	v_pk_fma_f32 v[82:83], v[188:189], v[34:35], v[82:83]
	v_pk_fma_f32 v[94:95], v[190:191], v[78:79], v[94:95]
	v_pk_fma_f32 v[82:83], v[190:191], v[32:33], v[82:83]
	v_pk_fma_f32 v[92:93], v[188:189], v[78:79], v[92:93]
	v_pk_fma_f32 v[82:83], v[192:193], v[30:31], v[82:83]
	v_pk_fma_f32 v[90:91], v[186:187], v[78:79], v[90:91]
	v_pk_fma_f32 v[82:83], v[194:195], v[28:29], v[82:83]
	v_pk_fma_f32 v[88:89], v[184:185], v[78:79], v[88:89]
	v_pk_fma_f32 v[140:141], v[198:199], v[26:27], v[82:83]
	v_pk_fma_f32 v[82:83], v[176:177], v[44:45], v[158:159]
	v_pk_fma_f32 v[86:87], v[188:189], v[72:73], v[86:87]
	v_pk_fma_f32 v[82:83], v[178:179], v[42:43], v[82:83]
	v_pk_fma_f32 v[84:85], v[186:187], v[72:73], v[84:85]
	v_pk_fma_f32 v[82:83], v[180:181], v[40:41], v[82:83]
	v_pk_fma_f32 v[98:99], v[198:199], v[76:77], v[98:99]
	v_pk_fma_f32 v[82:83], v[182:183], v[38:39], v[82:83]
	v_pk_fma_f32 v[96:97], v[194:195], v[76:77], v[96:97]
	v_pk_fma_f32 v[82:83], v[184:185], v[36:37], v[82:83]
	v_pk_fma_f32 v[94:95], v[192:193], v[76:77], v[94:95]
	v_pk_fma_f32 v[82:83], v[186:187], v[34:35], v[82:83]
	v_pk_fma_f32 v[92:93], v[190:191], v[76:77], v[92:93]
	v_pk_fma_f32 v[82:83], v[188:189], v[32:33], v[82:83]
	v_pk_fma_f32 v[90:91], v[188:189], v[76:77], v[90:91]
	v_pk_fma_f32 v[82:83], v[190:191], v[30:31], v[82:83]
	v_pk_fma_f32 v[88:89], v[186:187], v[76:77], v[88:89]
	v_pk_fma_f32 v[82:83], v[192:193], v[28:29], v[82:83]
	v_pk_fma_f32 v[86:87], v[190:191], v[70:71], v[86:87]
	v_pk_fma_f32 v[82:83], v[194:195], v[26:27], v[82:83]
	v_pk_fma_f32 v[84:85], v[188:189], v[70:71], v[84:85]
	v_pk_fma_f32 v[142:143], v[198:199], v[24:25], v[82:83]
	v_pk_fma_f32 v[82:83], v[176:177], v[42:43], v[168:169]
	v_pk_fma_f32 v[96:97], v[198:199], v[74:75], v[96:97]
	v_pk_fma_f32 v[82:83], v[178:179], v[40:41], v[82:83]
	v_pk_fma_f32 v[94:95], v[194:195], v[74:75], v[94:95]
	v_pk_fma_f32 v[82:83], v[180:181], v[38:39], v[82:83]
	v_pk_fma_f32 v[92:93], v[192:193], v[74:75], v[92:93]
	v_pk_fma_f32 v[82:83], v[182:183], v[36:37], v[82:83]
	v_pk_fma_f32 v[90:91], v[190:191], v[74:75], v[90:91]
	v_pk_fma_f32 v[82:83], v[184:185], v[34:35], v[82:83]
	v_pk_fma_f32 v[88:89], v[188:189], v[74:75], v[88:89]
	v_pk_fma_f32 v[82:83], v[186:187], v[32:33], v[82:83]
	v_pk_fma_f32 v[86:87], v[192:193], v[68:69], v[86:87]
	v_pk_fma_f32 v[82:83], v[188:189], v[30:31], v[82:83]
	v_pk_fma_f32 v[84:85], v[190:191], v[68:69], v[84:85]
	v_pk_fma_f32 v[82:83], v[190:191], v[28:29], v[82:83]
	v_pk_fma_f32 v[94:95], v[198:199], v[72:73], v[94:95]
	v_pk_fma_f32 v[82:83], v[192:193], v[26:27], v[82:83]
	v_pk_fma_f32 v[92:93], v[194:195], v[72:73], v[92:93]
	v_pk_fma_f32 v[82:83], v[194:195], v[24:25], v[82:83]
	v_pk_fma_f32 v[90:91], v[192:193], v[72:73], v[90:91]
	v_pk_fma_f32 v[144:145], v[198:199], v[22:23], v[82:83]
	v_pk_fma_f32 v[82:83], v[176:177], v[40:41], v[170:171]
	v_pk_fma_f32 v[88:89], v[190:191], v[72:73], v[88:89]
	v_pk_fma_f32 v[82:83], v[178:179], v[38:39], v[82:83]
	v_pk_fma_f32 v[86:87], v[194:195], v[66:67], v[86:87]
	v_pk_fma_f32 v[82:83], v[180:181], v[36:37], v[82:83]
	v_pk_fma_f32 v[84:85], v[192:193], v[66:67], v[84:85]
	v_pk_fma_f32 v[82:83], v[182:183], v[34:35], v[82:83]
	v_pk_fma_f32 v[92:93], v[198:199], v[70:71], v[92:93]
	v_pk_fma_f32 v[82:83], v[184:185], v[32:33], v[82:83]
	s_waitcnt vmcnt(0)
; __device__ __forceinline__ void conv_unit(unsigned char* ws, LAS unsigned char* lds, int t0) {
;     ...
;     for (int j = 0; j < CONVK; ++j) {
;         const f32x2 w = *(const f32x2*)(conv_w + j * CONVW + c0);
; #pragma unroll
;         for (int t = 0; t < 32; ++t) { a0[t] += w[0] * y0[t + j]; a1[t] += w[1] * y1[t + j]; }
;     }
;     const bf16_t* GC = (const bf16_t*)(ws + WS_GC);
;     unsigned gcv[32];
; #pragma unroll
;     for (int t = 0; t < 32; ++t) gcv[t] = *(const unsigned*)(GC + (size_t)(t0 + t) * CONVW + c0);
	v_pk_fma_f32 v[78:79], v[152:153], v[78:79], v[102:103]
	v_pk_fma_f32 v[82:83], v[186:187], v[30:31], v[82:83]
	v_pk_fma_f32 v[90:91], v[194:195], v[70:71], v[90:91]
	v_pk_fma_f32 v[82:83], v[188:189], v[28:29], v[82:83]
	v_pk_fma_f32 v[88:89], v[192:193], v[70:71], v[88:89]
	v_pk_fma_f32 v[82:83], v[190:191], v[26:27], v[82:83]
	v_pk_fma_f32 v[104:105], v[198:199], v[64:65], v[86:87]
	v_pk_fma_f32 v[82:83], v[192:193], v[24:25], v[82:83]
	v_pk_fma_f32 v[84:85], v[194:195], v[64:65], v[84:85]
	v_pk_fma_f32 v[82:83], v[194:195], v[22:23], v[82:83]
	v_pk_fma_f32 v[90:91], v[198:199], v[68:69], v[90:91]
	v_pk_fma_f32 v[146:147], v[198:199], v[20:21], v[82:83]
	v_pk_fma_f32 v[82:83], v[176:177], v[38:39], v[172:173]
	v_pk_fma_f32 v[88:89], v[194:195], v[68:69], v[88:89]
	v_pk_fma_f32 v[82:83], v[178:179], v[36:37], v[82:83]
	v_pk_fma_f32 v[106:107], v[198:199], v[62:63], v[84:85]
	v_pk_fma_f32 v[82:83], v[180:181], v[34:35], v[82:83]
	v_pk_fma_f32 v[88:89], v[198:199], v[66:67], v[88:89]
	v_pk_fma_f32 v[82:83], v[182:183], v[32:33], v[82:83]
	s_add_i32 s92, s24, 19
	v_pk_fma_f32 v[82:83], v[184:185], v[30:31], v[82:83]
	s_mov_b32 s93, s37
	v_pk_fma_f32 v[82:83], v[186:187], v[28:29], v[82:83]
	s_add_i32 s90, s24, 20
	v_pk_fma_f32 v[82:83], v[188:189], v[26:27], v[82:83]
	s_mov_b32 s91, s37
	v_pk_fma_f32 v[82:83], v[190:191], v[24:25], v[82:83]
	s_add_i32 s88, s24, 21
	v_pk_fma_f32 v[82:83], v[192:193], v[22:23], v[82:83]
	s_mov_b32 s89, s37
	v_pk_fma_f32 v[82:83], v[194:195], v[20:21], v[82:83]
	s_add_i32 s86, s24, 22
	v_pk_fma_f32 v[148:149], v[198:199], v[10:11], v[82:83]
	v_pk_fma_f32 v[82:83], v[176:177], v[36:37], v[174:175]
	s_mov_b32 s87, s37
	v_pk_fma_f32 v[82:83], v[178:179], v[34:35], v[82:83]
	s_add_i32 s84, s24, 23
	v_pk_fma_f32 v[82:83], v[180:181], v[32:33], v[82:83]
	s_mov_b32 s85, s37
	v_pk_fma_f32 v[82:83], v[182:183], v[30:31], v[82:83]
	s_add_i32 s82, s24, 24
	v_pk_fma_f32 v[82:83], v[184:185], v[28:29], v[82:83]
	s_mov_b32 s83, s37
	v_pk_fma_f32 v[82:83], v[186:187], v[26:27], v[82:83]
	s_add_i32 s80, s24, 25
	v_pk_fma_f32 v[82:83], v[188:189], v[24:25], v[82:83]
	s_mov_b32 s81, s37
	v_pk_fma_f32 v[82:83], v[190:191], v[22:23], v[82:83]
	s_add_i32 s78, s24, 26
	v_pk_fma_f32 v[82:83], v[192:193], v[20:21], v[82:83]
	s_mov_b32 s79, s37
	v_pk_fma_f32 v[82:83], v[194:195], v[10:11], v[82:83]
	s_add_i32 s76, s24, 27
	v_pk_fma_f32 v[150:151], v[198:199], v[8:9], v[82:83]
	v_add_co_u32_e32 v82, vcc, s19, v80
	s_mov_b32 s19, 0x1e000
	s_nop 0
	v_addc_co_u32_e32 v83, vcc, 0, v81, vcc
	global_load_dwordx2 v[154:155], v[82:83], off offset:-4096
	global_load_dwordx2 v[156:157], v[82:83], off
	v_add_co_u32_e32 v80, vcc, s19, v80
	s_mov_b32 s77, s37
	s_nop 0
	v_addc_co_u32_e32 v81, vcc, 0, v81, vcc
	global_load_dwordx2 v[158:159], v[80:81], off offset:-4096
	global_load_dwordx2 v[168:169], v[80:81], off
	s_add_i32 s74, s24, 28
	s_mov_b32 s75, s37
	s_add_i32 s72, s24, 29
	s_mov_b32 s73, s37
	s_add_i32 s70, s24, 30
	s_mov_b32 s71, s37
	s_add_i32 s68, s24, 31
	s_mov_b32 s69, s37
	s_add_i32 s66, s24, 32
	s_mov_b32 s67, s37
	s_add_i32 s64, s24, 33
	s_mov_b32 s65, s37
	s_add_i32 s62, s24, 34
	s_mov_b32 s63, s37
	s_add_i32 s60, s24, 35
	s_mov_b32 s61, s37
	s_add_i32 s58, s24, 36
	s_mov_b32 s59, s37
	s_add_i32 s56, s24, 37
	s_mov_b32 s57, s37
	s_add_i32 s54, s24, 38
	s_mov_b32 s55, s37
	s_add_i32 s52, s24, 39
	s_mov_b32 s53, s37
	s_add_i32 s50, s24, 40
	s_mov_b32 s51, s37
	s_add_i32 s48, s24, 41
	s_mov_b32 s49, s37
	s_add_i32 s46, s24, 42
	s_mov_b32 s47, s37
	s_add_i32 s44, s24, 43
	s_mov_b32 s45, s37
	s_add_i32 s42, s24, 44
	s_mov_b32 s43, s37
	s_add_i32 s40, s24, 45
	s_mov_b32 s41, s37
	s_add_i32 s18, s24, 46
	s_mov_b32 s19, s37
	s_waitcnt vmcnt(3)
	v_pk_fma_f32 v[78:79], v[154:155], v[76:77], v[78:79]
	v_pk_fma_f32 v[76:77], v[152:153], v[76:77], v[100:101]
	s_waitcnt vmcnt(2)
	v_pk_fma_f32 v[78:79], v[156:157], v[74:75], v[78:79]
	v_pk_fma_f32 v[76:77], v[154:155], v[74:75], v[76:77]
	v_pk_fma_f32 v[74:75], v[152:153], v[74:75], v[98:99]
	v_pk_fma_f32 v[76:77], v[156:157], v[72:73], v[76:77]
	s_waitcnt vmcnt(1)
	v_pk_fma_f32 v[78:79], v[158:159], v[72:73], v[78:79]
	v_pk_fma_f32 v[74:75], v[154:155], v[72:73], v[74:75]
	v_pk_fma_f32 v[72:73], v[152:153], v[72:73], v[96:97]
	s_waitcnt vmcnt(0)
; __device__ __forceinline__ void conv_unit(unsigned char* ws, LAS unsigned char* lds, int t0) {
;     ...
;     for (int j = 0; j < CONVK; ++j) {
;         const f32x2 w = *(const f32x2*)(conv_w + j * CONVW + c0);
; #pragma unroll
;         for (int t = 0; t < 32; ++t) { a0[t] += w[0] * y0[t + j]; a1[t] += w[1] * y1[t + j]; }
	v_pk_fma_f32 v[86:87], v[168:169], v[70:71], v[78:79]
	v_pk_fma_f32 v[76:77], v[158:159], v[70:71], v[76:77]
	v_pk_fma_f32 v[74:75], v[156:157], v[70:71], v[74:75]
	v_pk_fma_f32 v[72:73], v[154:155], v[70:71], v[72:73]
	v_pk_fma_f32 v[70:71], v[152:153], v[70:71], v[94:95]
	v_pk_fma_f32 v[84:85], v[168:169], v[68:69], v[76:77]
	v_pk_fma_f32 v[74:75], v[158:159], v[68:69], v[74:75]
	v_pk_fma_f32 v[72:73], v[156:157], v[68:69], v[72:73]
	v_pk_fma_f32 v[70:71], v[154:155], v[68:69], v[70:71]
	v_pk_fma_f32 v[68:69], v[152:153], v[68:69], v[92:93]
	v_pk_fma_f32 v[82:83], v[168:169], v[66:67], v[74:75]
	v_pk_fma_f32 v[72:73], v[158:159], v[66:67], v[72:73]
	v_pk_fma_f32 v[70:71], v[156:157], v[66:67], v[70:71]
	v_pk_fma_f32 v[68:69], v[154:155], v[66:67], v[68:69]
	v_pk_fma_f32 v[66:67], v[152:153], v[66:67], v[90:91]
	v_pk_fma_f32 v[80:81], v[168:169], v[64:65], v[72:73]
	v_pk_fma_f32 v[70:71], v[158:159], v[64:65], v[70:71]
	v_pk_fma_f32 v[68:69], v[156:157], v[64:65], v[68:69]
	v_pk_fma_f32 v[66:67], v[154:155], v[64:65], v[66:67]
	v_pk_fma_f32 v[64:65], v[152:153], v[64:65], v[88:89]
	v_pk_fma_f32 v[78:79], v[168:169], v[62:63], v[70:71]
	v_pk_fma_f32 v[68:69], v[158:159], v[62:63], v[68:69]
	v_pk_fma_f32 v[66:67], v[156:157], v[62:63], v[66:67]
	v_pk_fma_f32 v[64:65], v[154:155], v[62:63], v[64:65]
	v_pk_fma_f32 v[62:63], v[152:153], v[62:63], v[104:105]
	v_pk_fma_f32 v[76:77], v[168:169], v[60:61], v[68:69]
	v_pk_fma_f32 v[66:67], v[158:159], v[60:61], v[66:67]
	v_pk_fma_f32 v[64:65], v[156:157], v[60:61], v[64:65]
	v_pk_fma_f32 v[62:63], v[154:155], v[60:61], v[62:63]
	v_pk_fma_f32 v[60:61], v[152:153], v[60:61], v[106:107]
	v_pk_fma_f32 v[74:75], v[168:169], v[56:57], v[66:67]
	v_pk_fma_f32 v[64:65], v[158:159], v[56:57], v[64:65]
	v_pk_fma_f32 v[62:63], v[156:157], v[56:57], v[62:63]
	v_pk_fma_f32 v[60:61], v[154:155], v[56:57], v[60:61]
	v_pk_fma_f32 v[56:57], v[152:153], v[56:57], v[108:109]
	v_pk_fma_f32 v[72:73], v[168:169], v[54:55], v[64:65]
	v_pk_fma_f32 v[62:63], v[158:159], v[54:55], v[62:63]
	v_pk_fma_f32 v[60:61], v[156:157], v[54:55], v[60:61]
	v_pk_fma_f32 v[56:57], v[154:155], v[54:55], v[56:57]
	v_pk_fma_f32 v[54:55], v[152:153], v[54:55], v[110:111]
	v_pk_fma_f32 v[70:71], v[168:169], v[52:53], v[62:63]
	v_pk_fma_f32 v[60:61], v[158:159], v[52:53], v[60:61]
	v_pk_fma_f32 v[56:57], v[156:157], v[52:53], v[56:57]
	v_pk_fma_f32 v[54:55], v[154:155], v[52:53], v[54:55]
	v_pk_fma_f32 v[52:53], v[152:153], v[52:53], v[112:113]
	v_pk_fma_f32 v[68:69], v[168:169], v[50:51], v[60:61]
	v_pk_fma_f32 v[56:57], v[158:159], v[50:51], v[56:57]
	v_pk_fma_f32 v[54:55], v[156:157], v[50:51], v[54:55]
	v_pk_fma_f32 v[52:53], v[154:155], v[50:51], v[52:53]
	v_pk_fma_f32 v[50:51], v[152:153], v[50:51], v[114:115]
	v_pk_fma_f32 v[64:65], v[168:169], v[48:49], v[56:57]
	v_pk_fma_f32 v[54:55], v[158:159], v[48:49], v[54:55]
	v_pk_fma_f32 v[52:53], v[156:157], v[48:49], v[52:53]
	v_pk_fma_f32 v[50:51], v[154:155], v[48:49], v[50:51]
	v_pk_fma_f32 v[48:49], v[152:153], v[48:49], v[116:117]
	v_pk_fma_f32 v[62:63], v[168:169], v[46:47], v[54:55]
	v_pk_fma_f32 v[52:53], v[158:159], v[46:47], v[52:53]
	v_pk_fma_f32 v[50:51], v[156:157], v[46:47], v[50:51]
	v_pk_fma_f32 v[48:49], v[154:155], v[46:47], v[48:49]
	v_pk_fma_f32 v[46:47], v[152:153], v[46:47], v[118:119]
	v_pk_fma_f32 v[60:61], v[168:169], v[44:45], v[52:53]
	v_pk_fma_f32 v[50:51], v[158:159], v[44:45], v[50:51]
	v_pk_fma_f32 v[48:49], v[156:157], v[44:45], v[48:49]
	v_pk_fma_f32 v[46:47], v[154:155], v[44:45], v[46:47]
	v_pk_fma_f32 v[44:45], v[152:153], v[44:45], v[120:121]
	v_pk_fma_f32 v[56:57], v[168:169], v[42:43], v[50:51]
	v_pk_fma_f32 v[48:49], v[158:159], v[42:43], v[48:49]
	v_pk_fma_f32 v[46:47], v[156:157], v[42:43], v[46:47]
	v_pk_fma_f32 v[44:45], v[154:155], v[42:43], v[44:45]
	v_pk_fma_f32 v[42:43], v[152:153], v[42:43], v[122:123]
	v_pk_fma_f32 v[54:55], v[168:169], v[40:41], v[48:49]
	v_pk_fma_f32 v[46:47], v[158:159], v[40:41], v[46:47]
	v_pk_fma_f32 v[44:45], v[156:157], v[40:41], v[44:45]
	v_pk_fma_f32 v[42:43], v[154:155], v[40:41], v[42:43]
	v_pk_fma_f32 v[40:41], v[152:153], v[40:41], v[124:125]
	v_pk_fma_f32 v[52:53], v[168:169], v[38:39], v[46:47]
	v_pk_fma_f32 v[44:45], v[158:159], v[38:39], v[44:45]
	v_pk_fma_f32 v[42:43], v[156:157], v[38:39], v[42:43]
	v_pk_fma_f32 v[40:41], v[154:155], v[38:39], v[40:41]
	v_pk_fma_f32 v[38:39], v[152:153], v[38:39], v[126:127]
	v_pk_fma_f32 v[50:51], v[168:169], v[36:37], v[44:45]
	v_pk_fma_f32 v[42:43], v[158:159], v[36:37], v[42:43]
	v_pk_fma_f32 v[40:41], v[156:157], v[36:37], v[40:41]
	v_pk_fma_f32 v[38:39], v[154:155], v[36:37], v[38:39]
	v_pk_fma_f32 v[36:37], v[152:153], v[36:37], v[128:129]
	v_pk_fma_f32 v[48:49], v[168:169], v[34:35], v[42:43]
	v_pk_fma_f32 v[40:41], v[158:159], v[34:35], v[40:41]
	v_pk_fma_f32 v[38:39], v[156:157], v[34:35], v[38:39]
	v_pk_fma_f32 v[36:37], v[154:155], v[34:35], v[36:37]
	v_pk_fma_f32 v[34:35], v[152:153], v[34:35], v[130:131]
	v_pk_fma_f32 v[46:47], v[168:169], v[32:33], v[40:41]
	v_pk_fma_f32 v[38:39], v[158:159], v[32:33], v[38:39]
	v_pk_fma_f32 v[36:37], v[156:157], v[32:33], v[36:37]
	v_pk_fma_f32 v[34:35], v[154:155], v[32:33], v[34:35]
	v_pk_fma_f32 v[32:33], v[152:153], v[32:33], v[132:133]
	v_pk_fma_f32 v[44:45], v[168:169], v[30:31], v[38:39]
	v_pk_fma_f32 v[36:37], v[158:159], v[30:31], v[36:37]
	v_pk_fma_f32 v[34:35], v[156:157], v[30:31], v[34:35]
	v_pk_fma_f32 v[32:33], v[154:155], v[30:31], v[32:33]
	v_pk_fma_f32 v[30:31], v[152:153], v[30:31], v[134:135]
	v_pk_fma_f32 v[42:43], v[168:169], v[28:29], v[36:37]
	v_pk_fma_f32 v[34:35], v[158:159], v[28:29], v[34:35]
; __device__ __forceinline__ void conv_unit(unsigned char* ws, LAS unsigned char* lds, int t0) {
;     ...
;     for (int j = 0; j < CONVK; ++j) {
;         const f32x2 w = *(const f32x2*)(conv_w + j * CONVW + c0);
; #pragma unroll
;         for (int t = 0; t < 32; ++t) { a0[t] += w[0] * y0[t + j]; a1[t] += w[1] * y1[t + j]; }
;     }
;     const bf16_t* GC = (const bf16_t*)(ws + WS_GC);
;     unsigned gcv[32];
; #pragma unroll
;     for (int t = 0; t < 32; ++t) gcv[t] = *(const unsigned*)(GC + (size_t)(t0 + t) * CONVW + c0);
;     float v[64];
; #pragma unroll
;     for (int t = 0; t < 32; ++t) { v[t] = a0[t] + a1[t]; v[32 + t] = a0[t] * a0[t] + a1[t] * a1[t]; }
	v_pk_fma_f32 v[32:33], v[156:157], v[28:29], v[32:33]
	v_pk_fma_f32 v[30:31], v[154:155], v[28:29], v[30:31]
	v_pk_fma_f32 v[28:29], v[152:153], v[28:29], v[136:137]
	v_pk_fma_f32 v[40:41], v[168:169], v[26:27], v[34:35]
	v_pk_fma_f32 v[32:33], v[158:159], v[26:27], v[32:33]
	v_pk_fma_f32 v[30:31], v[156:157], v[26:27], v[30:31]
	v_pk_fma_f32 v[28:29], v[154:155], v[26:27], v[28:29]
	v_pk_fma_f32 v[26:27], v[152:153], v[26:27], v[138:139]
	v_pk_fma_f32 v[38:39], v[168:169], v[24:25], v[32:33]
	v_pk_fma_f32 v[30:31], v[158:159], v[24:25], v[30:31]
	v_pk_fma_f32 v[28:29], v[156:157], v[24:25], v[28:29]
	v_pk_fma_f32 v[26:27], v[154:155], v[24:25], v[26:27]
	v_pk_fma_f32 v[24:25], v[152:153], v[24:25], v[140:141]
	v_pk_fma_f32 v[36:37], v[168:169], v[22:23], v[30:31]
	v_pk_fma_f32 v[28:29], v[158:159], v[22:23], v[28:29]
	v_pk_fma_f32 v[26:27], v[156:157], v[22:23], v[26:27]
	v_pk_fma_f32 v[24:25], v[154:155], v[22:23], v[24:25]
	v_pk_fma_f32 v[22:23], v[152:153], v[22:23], v[142:143]
	v_pk_fma_f32 v[34:35], v[168:169], v[20:21], v[28:29]
	v_pk_fma_f32 v[26:27], v[158:159], v[20:21], v[26:27]
	v_pk_fma_f32 v[24:25], v[156:157], v[20:21], v[24:25]
	v_pk_fma_f32 v[22:23], v[154:155], v[20:21], v[22:23]
	v_pk_fma_f32 v[20:21], v[152:153], v[20:21], v[144:145]
	v_pk_fma_f32 v[32:33], v[168:169], v[10:11], v[26:27]
	v_pk_fma_f32 v[24:25], v[158:159], v[10:11], v[24:25]
	v_pk_fma_f32 v[22:23], v[156:157], v[10:11], v[22:23]
	v_pk_fma_f32 v[20:21], v[154:155], v[10:11], v[20:21]
	v_pk_fma_f32 v[10:11], v[152:153], v[10:11], v[146:147]
	v_pk_fma_f32 v[30:31], v[168:169], v[8:9], v[24:25]
	v_pk_fma_f32 v[22:23], v[158:159], v[8:9], v[22:23]
	v_pk_fma_f32 v[20:21], v[156:157], v[8:9], v[20:21]
	v_pk_fma_f32 v[10:11], v[154:155], v[8:9], v[10:11]
	v_pk_fma_f32 v[8:9], v[152:153], v[8:9], v[148:149]
	v_pk_fma_f32 v[28:29], v[168:169], v[6:7], v[22:23]
	v_pk_fma_f32 v[20:21], v[158:159], v[6:7], v[20:21]
	v_pk_fma_f32 v[10:11], v[156:157], v[6:7], v[10:11]
	v_pk_fma_f32 v[8:9], v[154:155], v[6:7], v[8:9]
	v_pk_fma_f32 v[6:7], v[152:153], v[6:7], v[150:151]
	v_pk_fma_f32 v[26:27], v[168:169], v[4:5], v[20:21]
	v_pk_fma_f32 v[10:11], v[158:159], v[4:5], v[10:11]
	v_pk_fma_f32 v[8:9], v[156:157], v[4:5], v[8:9]
	v_pk_fma_f32 v[4:5], v[154:155], v[4:5], v[6:7]
	v_pk_fma_f32 v[24:25], v[168:169], v[2:3], v[10:11]
	v_pk_fma_f32 v[8:9], v[158:159], v[2:3], v[8:9]
	v_pk_fma_f32 v[2:3], v[156:157], v[2:3], v[4:5]
	v_pk_fma_f32 v[22:23], v[168:169], v[0:1], v[8:9]
	v_pk_fma_f32 v[0:1], v[158:159], v[0:1], v[2:3]
	v_add_f32_e32 v2, v86, v87
	v_pk_fma_f32 v[20:21], v[168:169], v[58:59], v[0:1]
	v_lshl_add_u64 v[0:1], v[18:19], 0, s[20:21]
	s_lshl_b64 s[20:21], s[30:31], 11
	global_load_dword v119, v[0:1], off
	v_lshl_add_u64 v[0:1], v[18:19], 0, s[20:21]
	s_lshl_b64 s[20:21], s[96:97], 11
	global_load_dword v118, v[0:1], off
	v_lshl_add_u64 v[0:1], v[18:19], 0, s[20:21]
	s_lshl_b64 s[20:21], s[94:95], 11
	global_load_dword v117, v[0:1], off
	v_lshl_add_u64 v[0:1], v[18:19], 0, s[20:21]
	s_lshl_b64 s[20:21], s[92:93], 11
	global_load_dword v116, v[0:1], off
	v_lshl_add_u64 v[0:1], v[18:19], 0, s[20:21]
	s_lshl_b64 s[20:21], s[90:91], 11
	global_load_dword v115, v[0:1], off
	v_lshl_add_u64 v[0:1], v[18:19], 0, s[20:21]
	s_lshl_b64 s[20:21], s[88:89], 11
	global_load_dword v114, v[0:1], off
	v_lshl_add_u64 v[0:1], v[18:19], 0, s[20:21]
	s_lshl_b64 s[20:21], s[86:87], 11
	global_load_dword v113, v[0:1], off
	v_lshl_add_u64 v[0:1], v[18:19], 0, s[20:21]
	s_lshl_b64 s[20:21], s[84:85], 11
	global_load_dword v112, v[0:1], off
	v_lshl_add_u64 v[0:1], v[18:19], 0, s[20:21]
	s_lshl_b64 s[20:21], s[82:83], 11
	global_load_dword v111, v[0:1], off
	v_lshl_add_u64 v[0:1], v[18:19], 0, s[20:21]
	s_lshl_b64 s[20:21], s[80:81], 11
	global_load_dword v110, v[0:1], off
	v_lshl_add_u64 v[0:1], v[18:19], 0, s[20:21]
	s_lshl_b64 s[20:21], s[78:79], 11
	global_load_dword v109, v[0:1], off
	v_lshl_add_u64 v[0:1], v[18:19], 0, s[20:21]
	s_lshl_b64 s[20:21], s[76:77], 11
	global_load_dword v108, v[0:1], off
	v_lshl_add_u64 v[0:1], v[18:19], 0, s[20:21]
	s_lshl_b64 s[20:21], s[74:75], 11
	global_load_dword v107, v[0:1], off
	v_lshl_add_u64 v[0:1], v[18:19], 0, s[20:21]
	s_lshl_b64 s[20:21], s[72:73], 11
	global_load_dword v106, v[0:1], off
	v_lshl_add_u64 v[0:1], v[18:19], 0, s[20:21]
	s_lshl_b64 s[20:21], s[70:71], 11
	global_load_dword v105, v[0:1], off
	v_lshl_add_u64 v[0:1], v[18:19], 0, s[20:21]
	s_lshl_b64 s[20:21], s[68:69], 11
	global_load_dword v104, v[0:1], off
	v_lshl_add_u64 v[0:1], v[18:19], 0, s[20:21]
	s_lshl_b64 s[20:21], s[66:67], 11
	global_load_dword v103, v[0:1], off
	v_lshl_add_u64 v[0:1], v[18:19], 0, s[20:21]
	s_lshl_b64 s[20:21], s[64:65], 11
	global_load_dword v102, v[0:1], off
	v_lshl_add_u64 v[0:1], v[18:19], 0, s[20:21]
	s_lshl_b64 s[20:21], s[62:63], 11
	global_load_dword v101, v[0:1], off
	v_lshl_add_u64 v[0:1], v[18:19], 0, s[20:21]
	s_lshl_b64 s[20:21], s[60:61], 11
	global_load_dword v100, v[0:1], off
	v_lshl_add_u64 v[0:1], v[18:19], 0, s[20:21]
	s_lshl_b64 s[20:21], s[58:59], 11
	global_load_dword v99, v[0:1], off
	v_lshl_add_u64 v[0:1], v[18:19], 0, s[20:21]
	s_lshl_b64 s[20:21], s[56:57], 11
	global_load_dword v98, v[0:1], off
	v_lshl_add_u64 v[0:1], v[18:19], 0, s[20:21]
	s_lshl_b64 s[20:21], s[54:55], 11
	global_load_dword v97, v[0:1], off
	v_lshl_add_u64 v[0:1], v[18:19], 0, s[20:21]
	s_lshl_b64 s[20:21], s[52:53], 11
	global_load_dword v96, v[0:1], off
	v_lshl_add_u64 v[0:1], v[18:19], 0, s[20:21]
	s_lshl_b64 s[20:21], s[50:51], 11
	global_load_dword v95, v[0:1], off
	v_lshl_add_u64 v[0:1], v[18:19], 0, s[20:21]
	s_lshl_b64 s[20:21], s[48:49], 11
; __device__ __forceinline__ void conv_unit(unsigned char* ws, LAS unsigned char* lds, int t0) {
;     ...
;     unsigned gcv[32];
; #pragma unroll
;     for (int t = 0; t < 32; ++t) gcv[t] = *(const unsigned*)(GC + (size_t)(t0 + t) * CONVW + c0);
;     float v[64];
; #pragma unroll
;     for (int t = 0; t < 32; ++t) { v[t] = a0[t] + a1[t]; v[32 + t] = a0[t] * a0[t] + a1[t] * a1[t]; }
; #pragma unroll
;     for (int h = 32; h >= 1; h >>= 1) {
;         const bool up = (lane & h) != 0;
; #pragma unroll
;         for (int i = 0; i < h; ++i) {
;             const float send = up ? v[i] : v[i + h], keep = up ? v[i + h] : v[i];
;             v[i] = keep + __shfl_xor(send, h);
;         }
;     }
	global_load_dword v94, v[0:1], off
	v_lshl_add_u64 v[0:1], v[18:19], 0, s[20:21]
	s_lshl_b64 s[20:21], s[46:47], 11
	global_load_dword v93, v[0:1], off
	v_lshl_add_u64 v[0:1], v[18:19], 0, s[20:21]
	s_lshl_b64 s[20:21], s[44:45], 11
	global_load_dword v92, v[0:1], off
	v_lshl_add_u64 v[0:1], v[18:19], 0, s[20:21]
	s_lshl_b64 s[20:21], s[42:43], 11
	global_load_dword v90, v[0:1], off
	v_lshl_add_u64 v[0:1], v[18:19], 0, s[20:21]
	s_lshl_b64 s[20:21], s[40:41], 11
	global_load_dword v91, v[0:1], off
	v_lshl_add_u64 v[0:1], v[18:19], 0, s[20:21]
	s_lshl_b64 s[20:21], s[18:19], 11
	global_load_dword v89, v[0:1], off
	v_lshl_add_u64 v[0:1], v[18:19], 0, s[20:21]
	global_load_dword v88, v[0:1], off
	v_pk_mul_f32 v[0:1], v[86:87], v[86:87]
	v_add_f32_e32 v4, v84, v85
	v_add_f32_e32 v3, v0, v1
	v_pk_mul_f32 v[0:1], v[84:85], v[84:85]
	v_add_f32_e32 v6, v82, v83
	v_add_f32_e32 v5, v0, v1
	v_pk_mul_f32 v[0:1], v[82:83], v[82:83]
	v_add_f32_e32 v8, v80, v81
	v_add_f32_e32 v7, v0, v1
	v_pk_mul_f32 v[0:1], v[80:81], v[80:81]
	v_add_f32_e32 v10, v78, v79
	v_add_f32_e32 v9, v0, v1
	v_pk_mul_f32 v[0:1], v[78:79], v[78:79]
	v_add_f32_e32 v58, v76, v77
	v_add_f32_e32 v11, v0, v1
	v_pk_mul_f32 v[0:1], v[76:77], v[76:77]
	v_add_f32_e32 v66, v74, v75
	v_add_f32_e32 v59, v0, v1
	v_pk_mul_f32 v[0:1], v[74:75], v[74:75]
	v_add_f32_e32 v120, v72, v73
	v_add_f32_e32 v67, v0, v1
	v_pk_mul_f32 v[0:1], v[72:73], v[72:73]
	v_add_f32_e32 v122, v70, v71
	v_add_f32_e32 v121, v0, v1
	v_pk_mul_f32 v[0:1], v[70:71], v[70:71]
	v_add_f32_e32 v124, v68, v69
	v_add_f32_e32 v123, v0, v1
	v_pk_mul_f32 v[0:1], v[68:69], v[68:69]
	v_add_f32_e32 v126, v64, v65
	v_add_f32_e32 v125, v0, v1
	v_pk_mul_f32 v[0:1], v[64:65], v[64:65]
	v_add_f32_e32 v128, v62, v63
	v_add_f32_e32 v127, v0, v1
	v_pk_mul_f32 v[0:1], v[62:63], v[62:63]
	v_add_f32_e32 v130, v60, v61
	v_add_f32_e32 v129, v0, v1
	v_pk_mul_f32 v[0:1], v[60:61], v[60:61]
	v_add_f32_e32 v132, v56, v57
	v_add_f32_e32 v131, v0, v1
	v_pk_mul_f32 v[0:1], v[56:57], v[56:57]
	v_add_f32_e32 v134, v54, v55
	v_add_f32_e32 v133, v0, v1
	v_pk_mul_f32 v[0:1], v[54:55], v[54:55]
	v_add_f32_e32 v136, v52, v53
	v_add_f32_e32 v135, v0, v1
	v_pk_mul_f32 v[0:1], v[52:53], v[52:53]
	v_add_f32_e32 v138, v50, v51
	v_add_f32_e32 v137, v0, v1
	v_pk_mul_f32 v[0:1], v[50:51], v[50:51]
	v_add_f32_e32 v140, v48, v49
	v_add_f32_e32 v139, v0, v1
	v_pk_mul_f32 v[0:1], v[48:49], v[48:49]
	v_add_f32_e32 v142, v46, v47
	v_add_f32_e32 v141, v0, v1
	v_pk_mul_f32 v[0:1], v[46:47], v[46:47]
	v_add_f32_e32 v144, v44, v45
	v_add_f32_e32 v143, v0, v1
	v_pk_mul_f32 v[0:1], v[44:45], v[44:45]
	v_add_f32_e32 v146, v42, v43
	v_add_f32_e32 v145, v0, v1
	v_pk_mul_f32 v[0:1], v[42:43], v[42:43]
	v_add_f32_e32 v148, v40, v41
	v_add_f32_e32 v147, v0, v1
	v_pk_mul_f32 v[0:1], v[40:41], v[40:41]
	v_add_f32_e32 v150, v38, v39
	v_add_f32_e32 v149, v0, v1
	v_pk_mul_f32 v[0:1], v[38:39], v[38:39]
	v_add_f32_e32 v152, v36, v37
	v_add_f32_e32 v151, v0, v1
	v_pk_mul_f32 v[0:1], v[36:37], v[36:37]
	v_add_f32_e32 v154, v34, v35
	v_add_f32_e32 v153, v0, v1
	v_pk_mul_f32 v[0:1], v[34:35], v[34:35]
	v_add_f32_e32 v156, v32, v33
	v_add_f32_e32 v155, v0, v1
	v_pk_mul_f32 v[0:1], v[32:33], v[32:33]
	v_add_f32_e32 v158, v30, v31
	v_add_f32_e32 v157, v0, v1
	v_pk_mul_f32 v[0:1], v[30:31], v[30:31]
	v_add_f32_e32 v163, v28, v29
	v_add_f32_e32 v159, v0, v1
	v_pk_mul_f32 v[0:1], v[28:29], v[28:29]
	v_add_f32_e32 v168, v26, v27
	v_add_f32_e32 v167, v0, v1
	v_pk_mul_f32 v[0:1], v[26:27], v[26:27]
	v_add_f32_e32 v170, v24, v25
	v_add_f32_e32 v169, v0, v1
	v_pk_mul_f32 v[0:1], v[24:25], v[24:25]
	v_add_f32_e32 v172, v22, v23
	v_add_f32_e32 v171, v0, v1
	v_pk_mul_f32 v[0:1], v[22:23], v[22:23]
	v_add_f32_e32 v174, v20, v21
	v_add_f32_e32 v173, v0, v1
	v_pk_mul_f32 v[0:1], v[20:21], v[20:21]
	s_nop 0
	v_add_f32_e32 v175, v0, v1
	v_permlane32_swap_b32_e32 v2, v3
	v_permlane32_swap_b32_e32 v4, v5
	v_permlane32_swap_b32_e32 v6, v7
	v_permlane32_swap_b32_e32 v8, v9
	v_add_f32_e32 v2, v2, v3
	v_add_f32_e32 v4, v4, v5
	v_add_f32_e32 v6, v6, v7
	v_add_f32_e32 v8, v8, v9
	v_permlane32_swap_b32_e32 v10, v11
	v_permlane32_swap_b32_e32 v58, v59
	v_permlane32_swap_b32_e32 v66, v67
	v_permlane32_swap_b32_e32 v120, v121
	v_add_f32_e32 v10, v10, v11
	v_add_f32_e32 v58, v58, v59
	v_add_f32_e32 v66, v66, v67
	v_add_f32_e32 v120, v120, v121
	v_permlane32_swap_b32_e32 v122, v123
	v_permlane32_swap_b32_e32 v124, v125
	v_permlane32_swap_b32_e32 v126, v127
	v_permlane32_swap_b32_e32 v128, v129
	v_add_f32_e32 v122, v122, v123
	v_add_f32_e32 v124, v124, v125
	v_add_f32_e32 v126, v126, v127
	v_add_f32_e32 v128, v128, v129
	v_permlane32_swap_b32_e32 v130, v131
	v_permlane32_swap_b32_e32 v132, v133
	v_permlane32_swap_b32_e32 v134, v135
	v_permlane32_swap_b32_e32 v136, v137
	v_add_f32_e32 v130, v130, v131
	v_add_f32_e32 v132, v132, v133
	v_add_f32_e32 v134, v134, v135
	v_add_f32_e32 v136, v136, v137
	v_permlane32_swap_b32_e32 v138, v139
	v_permlane32_swap_b32_e32 v140, v141
	v_permlane32_swap_b32_e32 v142, v143
	v_permlane32_swap_b32_e32 v144, v145
	v_add_f32_e32 v138, v138, v139
	v_add_f32_e32 v140, v140, v141
	v_add_f32_e32 v142, v142, v143
	v_add_f32_e32 v144, v144, v145
	v_permlane32_swap_b32_e32 v146, v147
	v_permlane32_swap_b32_e32 v148, v149
	v_permlane32_swap_b32_e32 v150, v151
	v_permlane32_swap_b32_e32 v152, v153
	v_add_f32_e32 v146, v146, v147
	v_add_f32_e32 v148, v148, v149
; #define LAS __attribute__((address_space(3)))
; __device__ __forceinline__ void conv_unit(unsigned char* ws, LAS unsigned char* lds, int t0) {
;     ...
; #pragma unroll
;     for (int h = 32; h >= 1; h >>= 1) {
;         const bool up = (lane & h) != 0;
; #pragma unroll
;         for (int i = 0; i < h; ++i) {
;             const float send = up ? v[i] : v[i + h], keep = up ? v[i + h] : v[i];
;             v[i] = keep + __shfl_xor(send, h);
;         }
;     }
;     LAS float* red = (LAS float*)lds;
;     LAS float* stat = red + 512;
;     red[wid * 64 + lane] = v[0];
;     __syncthreads();
;     if (tid < 32) {
;         float s1 = 0.f, s2 = 0.f;
; #pragma unroll
;         for (int w = 0; w < 8; ++w) { s1 += red[w * 64 + tid]; s2 += red[w * 64 + 32 + tid]; }
;         const float mean = s1 * (1.0f / CONVW), var = fmaxf(s2 * (1.0f / CONVW) - mean * mean, 0.f);
;         stat[tid * 2] = mean; stat[tid * 2 + 1] = __builtin_amdgcn_rsqf(var + EPS);
;     }
	v_add_f32_e32 v150, v150, v151
	v_add_f32_e32 v152, v152, v153
	v_permlane32_swap_b32_e32 v154, v155
	v_permlane32_swap_b32_e32 v156, v157
	v_permlane32_swap_b32_e32 v158, v159
	v_permlane32_swap_b32_e32 v163, v167
	v_add_f32_e32 v154, v154, v155
	v_add_f32_e32 v156, v156, v157
	v_add_f32_e32 v158, v158, v159
	v_add_f32_e32 v163, v163, v167
	v_permlane32_swap_b32_e32 v168, v169
	v_permlane32_swap_b32_e32 v170, v171
	v_permlane32_swap_b32_e32 v172, v173
	v_permlane32_swap_b32_e32 v174, v175
	v_add_f32_e32 v168, v168, v169
	v_add_f32_e32 v170, v170, v171
	v_add_f32_e32 v172, v172, v173
	v_add_f32_e32 v174, v174, v175
	v_permlane16_swap_b32_e32 v2, v138
	v_permlane16_swap_b32_e32 v4, v140
	v_permlane16_swap_b32_e32 v6, v142
	v_permlane16_swap_b32_e32 v8, v144
	v_add_f32_e32 v2, v2, v138
	v_add_f32_e32 v4, v4, v140
	v_add_f32_e32 v6, v6, v142
	v_add_f32_e32 v8, v8, v144
	v_permlane16_swap_b32_e32 v10, v146
	v_permlane16_swap_b32_e32 v58, v148
	v_permlane16_swap_b32_e32 v66, v150
	v_permlane16_swap_b32_e32 v120, v152
	v_add_f32_e32 v10, v10, v146
	v_add_f32_e32 v58, v58, v148
	v_add_f32_e32 v66, v66, v150
	v_add_f32_e32 v120, v120, v152
	v_permlane16_swap_b32_e32 v122, v154
	v_permlane16_swap_b32_e32 v124, v156
	v_permlane16_swap_b32_e32 v126, v158
	v_permlane16_swap_b32_e32 v128, v163
	v_add_f32_e32 v122, v122, v154
	v_add_f32_e32 v124, v124, v156
	v_add_f32_e32 v126, v126, v158
	v_add_f32_e32 v128, v128, v163
	v_permlane16_swap_b32_e32 v130, v168
	v_permlane16_swap_b32_e32 v132, v170
	v_permlane16_swap_b32_e32 v134, v172
	v_permlane16_swap_b32_e32 v136, v174
	v_add_f32_e32 v130, v130, v168
	v_add_f32_e32 v132, v132, v170
	v_add_f32_e32 v134, v134, v172
	v_add_f32_e32 v136, v136, v174
	v_cndmask_b32_e64 v3, v2, v122, s[8:9]
	v_cndmask_b32_e64 v123, v122, v2, s[8:9]
	v_cndmask_b32_e64 v5, v4, v124, s[8:9]
	v_cndmask_b32_e64 v125, v124, v4, s[8:9]
	v_cndmask_b32_e64 v7, v6, v126, s[8:9]
	v_cndmask_b32_e64 v127, v126, v6, s[8:9]
	v_cndmask_b32_e64 v9, v8, v128, s[8:9]
	v_cndmask_b32_e64 v129, v128, v8, s[8:9]
	v_cndmask_b32_e64 v11, v10, v130, s[8:9]
	v_cndmask_b32_e64 v131, v130, v10, s[8:9]
	v_cndmask_b32_e64 v59, v58, v132, s[8:9]
	v_cndmask_b32_e64 v133, v132, v58, s[8:9]
	v_cndmask_b32_e64 v67, v66, v134, s[8:9]
	v_cndmask_b32_e64 v135, v134, v66, s[8:9]
	v_cndmask_b32_e64 v121, v120, v136, s[8:9]
	v_cndmask_b32_e64 v137, v136, v120, s[8:9]
	v_add_f32_dpp v2, v3, v123 row_ror:8 row_mask:0xf bank_mask:0xf
	v_add_f32_dpp v4, v5, v125 row_ror:8 row_mask:0xf bank_mask:0xf
	v_add_f32_dpp v6, v7, v127 row_ror:8 row_mask:0xf bank_mask:0xf
	v_add_f32_dpp v8, v9, v129 row_ror:8 row_mask:0xf bank_mask:0xf
	v_add_f32_dpp v10, v11, v131 row_ror:8 row_mask:0xf bank_mask:0xf
	v_add_f32_dpp v58, v59, v133 row_ror:8 row_mask:0xf bank_mask:0xf
	v_add_f32_dpp v66, v67, v135 row_ror:8 row_mask:0xf bank_mask:0xf
	v_add_f32_dpp v120, v121, v137 row_ror:8 row_mask:0xf bank_mask:0xf
	v_cndmask_b32_e64 v3, v2, v10, s[10:11]
	v_cndmask_b32_e64 v11, v10, v2, s[10:11]
	v_cndmask_b32_e64 v5, v4, v58, s[10:11]
	v_cndmask_b32_e64 v59, v58, v4, s[10:11]
	v_cndmask_b32_e64 v7, v6, v66, s[10:11]
	v_cndmask_b32_e64 v67, v66, v6, s[10:11]
	v_cndmask_b32_e64 v9, v8, v120, s[10:11]
	v_cndmask_b32_e64 v121, v120, v8, s[10:11]
	ds_swizzle_b32 v3, v3 offset:0x101f
	ds_swizzle_b32 v5, v5 offset:0x101f
	ds_swizzle_b32 v7, v7 offset:0x101f
	ds_swizzle_b32 v9, v9 offset:0x101f
	s_waitcnt lgkmcnt(0)
	v_add_f32_e32 v2, v11, v3
	v_add_f32_e32 v4, v59, v5
	v_add_f32_e32 v6, v67, v7
	v_add_f32_e32 v8, v121, v9
	v_cndmask_b32_e64 v3, v2, v6, s[12:13]
	v_cndmask_b32_e64 v7, v6, v2, s[12:13]
	v_cndmask_b32_e64 v5, v4, v8, s[12:13]
	v_cndmask_b32_e64 v9, v8, v4, s[12:13]
	s_nop 0
	v_add_f32_dpp v2, v3, v7 quad_perm:[2,3,0,1] row_mask:0xf bank_mask:0xf
	v_add_f32_dpp v4, v5, v9 quad_perm:[2,3,0,1] row_mask:0xf bank_mask:0xf
	v_cndmask_b32_e64 v3, v2, v4, s[14:15]
	v_cndmask_b32_e64 v5, v4, v2, s[14:15]
	s_nop 1
	v_add_f32_dpp v0, v3, v5 quad_perm:[1,0,3,2] row_mask:0xf bank_mask:0xf
	ds_write_b32 v13, v0
	s_waitcnt lgkmcnt(0)
	s_barrier
	s_and_saveexec_b64 s[20:21], s[16:17]
	s_cbranch_execz .LBB0_439
	ds_read2_b32 v[0:1], v13 offset1:32
	v_add_u32_e32 v4, 0x400, v13
	s_mov_b32 s28, 0x3a800000
	s_waitcnt lgkmcnt(0)
	v_add_f32_e32 v2, 0, v0
	v_add_f32_e32 v3, 0, v1
	ds_read2_b32 v[0:1], v13 offset0:64 offset1:96
	s_waitcnt lgkmcnt(0)
	v_add_f32_e32 v2, v2, v0
	v_add_f32_e32 v3, v3, v1
	ds_read2_b32 v[0:1], v13 offset0:128 offset1:160
	s_waitcnt lgkmcnt(0)
	v_add_f32_e32 v2, v2, v0
	v_add_f32_e32 v3, v3, v1
	ds_read2_b32 v[0:1], v13 offset0:192 offset1:224
	s_waitcnt lgkmcnt(0)
	v_add_f32_e32 v2, v2, v0
	v_add_f32_e32 v3, v3, v1
	ds_read2_b32 v[0:1], v4 offset1:32
	s_waitcnt lgkmcnt(0)
	v_add_f32_e32 v2, v2, v0
	v_add_f32_e32 v3, v3, v1
	ds_read2_b32 v[0:1], v4 offset0:64 offset1:96
	s_waitcnt lgkmcnt(0)
	v_add_f32_e32 v2, v2, v0
	v_add_f32_e32 v3, v3, v1
	ds_read2_b32 v[0:1], v4 offset0:128 offset1:160
	s_waitcnt lgkmcnt(0)
	v_add_f32_e32 v2, v2, v0
	v_add_f32_e32 v3, v3, v1
	ds_read2_b32 v[0:1], v4 offset0:192 offset1:224
	s_waitcnt lgkmcnt(0)
	v_add_f32_e32 v0, v2, v0
	v_mul_f32_e32 v0, 0x3a800000, v0
	v_add_f32_e32 v1, v3, v1
	v_mul_f32_e32 v2, v0, v0
	v_fma_f32 v1, v1, s28, -v2
	v_max_f32_e32 v1, 0, v1
	v_add_f32_e32 v1, 0x358637bd, v1
	v_rsq_f32_e32 v1, v1
	v_add_u32_e32 v2, v13, v166
	ds_write_b64 v2, v[0:1] offset:2048
	s_branch .LBB0_439
